# combo13 + QKV epilogue RMS-norm xor16/xor32 butterfly steps via v_permlane16_swap / v_permlane32_swap instead of ds_bpermute round trips
# speedup vs baseline: 1.0149x; 1.0061x over previous
;     __device__ __forceinline__ void operator()(const f32x4 (&acc)[2][2][4][2], const Unit& u, int wr, int wc, int fr, int fq) const {
;         const int row0 = u.pm * BM + wr * 64 + fr;
;         if (u.pn < 2) {
;             const int head = 4 * u.pn + wc; const bool isq = head < 6;
;             const float* g = isq ? gq : gk; const float gs = isq ? C2 : 1.0f;
;             f32x4 gv[2][2];
; #pragma unroll
;             for (int bj = 0; bj < 2; ++bj)
; #pragma unroll
;                 for (int n = 0; n < 2; ++n) gv[bj][n] = *(const f32x4*)(g + 32 * bj + 8 * fq + 4 * n) * gs;
;             const int ocol = 64 * head + 8 * fq;
; #pragma unroll
;             for (int ai = 0; ai < 2; ++ai)
; #pragma unroll
;                 for (int m = 0; m < 4; ++m) {
;                     const int row = row0 + ai * HALF + m * 16;
;                     const int w = row >= RPB ? row - RPB : row;
;                     f32x4 x[2][2]; float ss = 0.f;
; #pragma unroll
;                     for (int bj = 0; bj < 2; ++bj)
; #pragma unroll
;                         for (int n = 0; n < 2; ++n) { x[bj][n] = acc[ai][bj][m][n]; const f32x4 q = x[bj][n] * x[bj][n]; ss += (q[0] + q[1]) + (q[2] + q[3]); }
;                     ss += __shfl_xor(ss, 16); ss += __shfl_xor(ss, 32);
;                     const float rinv = 1.0f / sqrtf(ss * (1.0f / 64.0f) + LN_EPS);
; #pragma unroll
;                     for (int bj = 0; bj < 2; ++bj)
; #pragma unroll
;                         for (int n = 0; n < 2; ++n) x[bj][n] = x[bj][n] * rinv * gv[bj][n];
;                     if (w < SEQ) {
.LBB0_257:
	s_and_b64 vcc, exec, s[0:1]
	s_cbranch_vccz .LBB0_341
	s_lshl_b32 s0, s24, 2
	s_or_b32 s2, s0, s40
	s_cmp_lt_i32 s2, 6
	s_cselect_b64 vcc, -1, 0
	v_readlane_b32 s44, v253, 25
	s_and_b64 s[0:1], vcc, exec
	v_readlane_b32 s50, v253, 31
	v_readlane_b32 s51, v253, 32
	v_readlane_b32 s52, v253, 33
	v_readlane_b32 s53, v253, 34
	s_cselect_b32 s3, s51, s53
	s_cselect_b32 s8, s50, s52
	s_lshl_b64 s[0:1], s[60:61], 2
	s_add_u32 s0, s8, s0
	s_addc_u32 s1, s3, s1
	global_load_dwordx4 v[134:137], v172, s[0:1]
	global_load_dwordx4 v[138:141], v172, s[0:1] offset:16
	global_load_dwordx4 v[166:169], v172, s[0:1] offset:128
	global_load_dwordx4 v[176:179], v172, s[0:1] offset:144
	v_and_b32_e32 v186, 64, v220
	v_pk_mul_f32 v[158:159], v[132:133], v[132:133]
	v_pk_mul_f32 v[160:161], v[130:131], v[130:131]
	v_pk_mul_f32 v[162:163], v[128:129], v[128:129]
	v_pk_mul_f32 v[164:165], v[126:127], v[126:127]
	v_add_u32_e32 v189, 64, v186
	v_pk_mov_b32 v[186:187], v[160:161], v[158:159] op_sel:[1,0]
	v_mov_b32_e32 v161, v159
	v_pk_mov_b32 v[158:159], v[164:165], v[162:163] op_sel:[1,0]
	v_mov_b32_e32 v165, v163
	v_pk_add_f32 v[160:161], v[186:187], v[160:161]
	v_pk_add_f32 v[158:159], v[158:159], v[164:165]
	v_pk_mul_f32 v[174:175], v[124:125], v[124:125]
	v_pk_mul_f32 v[180:181], v[122:123], v[122:123]
	v_pk_mul_f32 v[182:183], v[120:121], v[120:121]
	v_pk_mul_f32 v[184:185], v[118:119], v[118:119]
	v_pk_add_f32 v[160:161], v[160:161], v[160:161] op_sel_hi:[0,1]
	v_pk_add_f32 v[158:159], v[158:159], v[158:159] op_sel_hi:[0,1]
	v_xor_b32_e32 v188, 16, v220
	v_add_f32_e32 v163, v180, v181
	v_add_f32_e32 v175, v174, v175
	v_mov_b32_e32 v162, v184
	v_mov_b32_e32 v174, v185
	v_mov_b32_e32 v158, v182
	v_mov_b32_e32 v160, v183
	v_cndmask_b32_e32 v0, 1.0, v219, vcc
	v_cmp_lt_i32_e32 vcc, v188, v189
	v_pk_add_f32 v[162:163], v[162:163], v[174:175]
	v_pk_add_f32 v[158:159], v[158:159], v[160:161]
	v_cndmask_b32_e32 v180, v220, v188, vcc
	v_pk_add_f32 v[158:159], v[162:163], v[158:159]
	v_lshlrev_b32_e32 v175, 2, v180
	v_add_f32_e32 v158, v158, v159
	v_mov_b32_e32 v159, v158
	v_mov_b32_e32 v248, v158
	s_nop 1
	v_permlane16_swap_b32_e32 v159, v248
	v_xor_b32_e32 v160, 32, v220
	v_cmp_lt_i32_e32 vcc, v160, v189
	v_add_u32_e32 v183, 0xffffdf00, v173
	v_readlane_b32 s45, v253, 26
	v_cndmask_b32_e32 v160, v220, v160, vcc
	v_lshlrev_b32_e32 v174, 2, v160
	s_waitcnt lgkmcnt(0)
	v_add_f32_e32 v158, v159, v248
	v_mov_b32_e32 v159, v158
	v_mov_b32_e32 v249, v158
	s_nop 1
	v_permlane32_swap_b32_e32 v159, v249
	v_readlane_b32 s46, v253, 27
	v_readlane_b32 s47, v253, 28
	v_readlane_b32 s48, v253, 29
	v_readlane_b32 s49, v253, 30
	s_waitcnt lgkmcnt(0)
	v_add_f32_e32 v158, v159, v249
	v_fmamk_f32 v158, v158, 0x3c800000, v216
	v_mul_f32_e32 v159, 0x4f800000, v158
	v_cmp_gt_f32_e32 vcc, s69, v158
	v_readlane_b32 s54, v253, 35
	v_readlane_b32 s55, v253, 36
	v_cndmask_b32_e32 v158, v158, v159, vcc
	v_sqrt_f32_e32 v159, v158
	v_readlane_b32 s56, v253, 37
	v_readlane_b32 s57, v253, 38
	v_readlane_b32 s58, v253, 39
	v_add_u32_e32 v160, -1, v159
	v_add_u32_e32 v161, 1, v159
	v_fma_f32 v162, -v160, v159, v158
	v_fma_f32 v163, -v161, v159, v158
	v_cmp_ge_f32_e64 s[0:1], 0, v162
	v_readlane_b32 s59, v253, 40
	s_waitcnt vmcnt(0)
	v_pk_mul_f32 v[164:165], v[0:1], v[134:135] op_sel_hi:[0,1]
	v_cndmask_b32_e64 v159, v159, v160, s[0:1]
	v_cmp_lt_f32_e64 s[0:1], 0, v163
	v_pk_mul_f32 v[162:163], v[0:1], v[136:137] op_sel_hi:[0,1]
	v_pk_mul_f32 v[134:135], v[0:1], v[178:179] op_sel_hi:[0,1]
	v_cndmask_b32_e64 v159, v159, v161, s[0:1]
	v_mul_f32_e32 v160, 0x37800000, v159
	v_cndmask_b32_e32 v159, v159, v160, vcc
	v_cmp_class_f32_e32 vcc, v158, v217
	v_pk_mul_f32 v[160:161], v[0:1], v[138:139] op_sel_hi:[0,1]
	v_pk_mul_f32 v[138:139], v[0:1], v[168:169] op_sel_hi:[0,1]
	v_cndmask_b32_e32 v180, v159, v158, vcc
	v_div_scale_f32 v181, s[0:1], v180, v180, 1.0
	v_rcp_f32_e32 v182, v181
	v_div_scale_f32 v184, vcc, 1.0, v180, 1.0
	v_pk_mul_f32 v[136:137], v[0:1], v[176:177] op_sel_hi:[0,1]
	v_fma_f32 v158, -v181, v182, 1.0
	v_fmac_f32_e32 v182, v158, v182
	v_mul_f32_e32 v185, v184, v182
	v_pk_mul_f32 v[158:159], v[0:1], v[140:141] op_sel_hi:[0,1]
	v_pk_mul_f32 v[140:141], v[0:1], v[166:167] op_sel_hi:[0,1]
	v_fma_f32 v0, -v181, v185, v184
	v_fmac_f32_e32 v185, v0, v182
	v_fma_f32 v0, -v181, v185, v184
	v_div_fmas_f32 v0, v0, v182, v185
	v_div_fixup_f32 v0, v0, v180, 1.0
	v_pk_mul_f32 v[166:167], v[130:131], v[0:1] op_sel_hi:[1,0]
	v_pk_mul_f32 v[130:131], v[132:133], v[0:1] op_sel_hi:[1,0]
	v_pk_mul_f32 v[132:133], v[164:165], v[166:167]
	v_pk_mul_f32 v[166:167], v[126:127], v[0:1] op_sel_hi:[1,0]
	v_cmp_lt_i32_e32 vcc, s67, v173
	v_pk_mul_f32 v[126:127], v[128:129], v[0:1] op_sel_hi:[1,0]
	v_pk_mul_f32 v[128:129], v[160:161], v[166:167]
	v_pk_mul_f32 v[166:167], v[122:123], v[0:1] op_sel_hi:[1,0]
	v_pk_mul_f32 v[122:123], v[124:125], v[0:1] op_sel_hi:[1,0]
	v_pk_mul_f32 v[118:119], v[118:119], v[0:1] op_sel_hi:[1,0]
	v_pk_mul_f32 v[120:121], v[120:121], v[0:1] op_sel_hi:[1,0]
	v_cndmask_b32_e32 v0, v173, v183, vcc
	v_pk_mul_f32 v[130:131], v[162:163], v[130:131]
	v_pk_mul_f32 v[126:127], v[158:159], v[126:127]
	v_pk_mul_f32 v[122:123], v[138:139], v[122:123]
	v_pk_mul_f32 v[168:169], v[140:141], v[166:167]
	v_pk_mul_f32 v[124:125], v[134:135], v[120:121]
	v_pk_mul_f32 v[166:167], v[136:137], v[118:119]
	v_cmp_gt_i32_e32 vcc, s66, v0
	s_and_saveexec_b64 s[0:1], vcc
	s_cbranch_execz .LBB0_260
; __device__ __forceinline__ unsigned cvt_pk_bf16(float lo, float hi) { unsigned r; asm volatile("v_cvt_pk_bf16_f32 %0, %1, %2" : "=v"(r) : "v"(lo), "v"(hi)); return r; }
;     __device__ __forceinline__ void operator()(const f32x4 (&acc)[2][2][4][2], const Unit& u, int wr, int wc, int fr, int fq) const {
;     ...
;                     f32x4 x[2][2]; float ss = 0.f;
; #pragma unroll
;                     for (int bj = 0; bj < 2; ++bj)
; #pragma unroll
;                         for (int n = 0; n < 2; ++n) { x[bj][n] = acc[ai][bj][m][n]; const f32x4 q = x[bj][n] * x[bj][n]; ss += (q[0] + q[1]) + (q[2] + q[3]); }
;                     ss += __shfl_xor(ss, 16); ss += __shfl_xor(ss, 32);
;                     const float rinv = 1.0f / sqrtf(ss * (1.0f / 64.0f) + LN_EPS);
; #pragma unroll
;                     for (int bj = 0; bj < 2; ++bj)
; #pragma unroll
;                         for (int n = 0; n < 2; ++n) x[bj][n] = x[bj][n] * rinv * gv[bj][n];
;                     if (w < SEQ) {
; #pragma unroll
;                         for (int bj = 0; bj < 2; ++bj) {
;                             const int pos = bj ? (w & 63) : (w >> 6);
; #pragma unroll
;                             for (int n = 0; n < 2; ++n) {
;                                 const f32x4 cs = *(const f32x4*)(tcos + pos * 16 + 8 * (fq & 1) + 4 * n);
;                                 const f32x4 sn = *(const f32x4*)(tsin + pos * 16 + 8 * (fq & 1) + 4 * n);
;                                 f32x4 p; p[0] = __shfl_xor(x[bj][n][0], 32); p[1] = __shfl_xor(x[bj][n][1], 32); p[2] = __shfl_xor(x[bj][n][2], 32); p[3] = __shfl_xor(x[bj][n][3], 32);
;                                 const f32x4 sgn = (fq < 2) ? -sn : sn;
;                                 x[bj][n] = x[bj][n] * cs + p * sgn;
;                             }
;                         }
;                     }
;                     bf16_t* rowp = O + (size_t)row * DIN + ocol;
; #pragma unroll
;                     for (int bj = 0; bj < 2; ++bj) { u32x4 wv; wv.x = cvt_pk_bf16(x[bj][0][0], x[bj][0][1]); wv.y = cvt_pk_bf16(x[bj][0][2], x[bj][0][3]); wv.z = cvt_pk_bf16(x[bj][1][0], x[bj][1][1]); wv.w = cvt_pk_bf16(x[bj][1][2], x[bj][1][3]);
	v_ashrrev_i32_e32 v118, 2, v0
	v_and_b32_e32 v118, -16, v118
	v_ashrrev_i32_e32 v119, 31, v118
	v_lshlrev_b64 v[118:119], 2, v[118:119]
	v_lshl_add_u64 v[180:181], v[150:151], 0, v[118:119]
	v_lshl_add_u64 v[182:183], v[152:153], 0, v[118:119]
	flat_load_dwordx4 v[118:121], v[180:181]
	flat_load_dwordx4 v[176:179], v[182:183]
	flat_load_dwordx4 v[240:243], v[180:181] offset:16
	flat_load_dwordx4 v[244:247], v[182:183] offset:16
	ds_bpermute_b32 v184, v174, v132
	ds_bpermute_b32 v185, v174, v133
	ds_bpermute_b32 v186, v174, v130
	ds_bpermute_b32 v187, v174, v131
	v_lshlrev_b32_e32 v0, 6, v0
	v_and_b32_e32 v0, 0x3c0, v0
	s_waitcnt vmcnt(0) lgkmcnt(0)
	v_xor_b32_e32 v188, 0x80000000, v176
	v_xor_b32_e32 v189, 0x80000000, v177
	v_xor_b32_e32 v190, 0x80000000, v178
	v_xor_b32_e32 v191, 0x80000000, v179
	v_cndmask_b32_e64 v179, v179, v191, s[4:5]
	v_cndmask_b32_e64 v178, v178, v190, s[4:5]
	v_cndmask_b32_e64 v177, v177, v189, s[4:5]
	v_cndmask_b32_e64 v176, v176, v188, s[4:5]
	v_pk_mul_f32 v[176:177], v[176:177], v[184:185]
	v_pk_mul_f32 v[178:179], v[178:179], v[186:187]
	v_pk_fma_f32 v[132:133], v[132:133], v[118:119], v[176:177]
	v_pk_fma_f32 v[130:131], v[130:131], v[120:121], v[178:179]
	ds_bpermute_b32 v180, v174, v128
	ds_bpermute_b32 v181, v174, v129
	ds_bpermute_b32 v182, v174, v126
	ds_bpermute_b32 v183, v174, v127
	s_waitcnt vmcnt(0) lgkmcnt(0)
	v_xor_b32_e32 v184, 0x80000000, v244
	v_xor_b32_e32 v185, 0x80000000, v245
	v_xor_b32_e32 v186, 0x80000000, v246
	v_xor_b32_e32 v187, 0x80000000, v247
	v_cndmask_b32_e64 v247, v247, v187, s[4:5]
	v_cndmask_b32_e64 v246, v246, v186, s[4:5]
	v_cndmask_b32_e64 v245, v245, v185, s[4:5]
	v_cndmask_b32_e64 v244, v244, v184, s[4:5]
	v_pk_mul_f32 v[244:245], v[244:245], v[180:181]
	v_pk_mul_f32 v[246:247], v[246:247], v[182:183]
	v_lshl_add_u64 v[180:181], v[150:151], 0, v[0:1]
	v_pk_fma_f32 v[126:127], v[126:127], v[242:243], v[246:247]
	v_pk_fma_f32 v[128:129], v[128:129], v[240:241], v[244:245]
	v_lshl_add_u64 v[182:183], v[152:153], 0, v[0:1]
	flat_load_dwordx4 v[118:121], v[180:181]
	flat_load_dwordx4 v[176:179], v[182:183]
	flat_load_dwordx4 v[240:243], v[180:181] offset:16
	flat_load_dwordx4 v[244:247], v[182:183] offset:16
	ds_bpermute_b32 v184, v174, v168
	ds_bpermute_b32 v185, v174, v169
	ds_bpermute_b32 v186, v174, v122
	ds_bpermute_b32 v187, v174, v123
	s_waitcnt vmcnt(0) lgkmcnt(0)
	v_xor_b32_e32 v0, 0x80000000, v176
	v_xor_b32_e32 v188, 0x80000000, v177
	v_xor_b32_e32 v189, 0x80000000, v178
	v_xor_b32_e32 v190, 0x80000000, v179
	v_cndmask_b32_e64 v179, v179, v190, s[4:5]
	v_cndmask_b32_e64 v178, v178, v189, s[4:5]
	v_cndmask_b32_e64 v177, v177, v188, s[4:5]
	v_cndmask_b32_e64 v176, v176, v0, s[4:5]
	v_pk_mul_f32 v[176:177], v[176:177], v[184:185]
	v_pk_mul_f32 v[178:179], v[178:179], v[186:187]
	v_pk_fma_f32 v[168:169], v[168:169], v[118:119], v[176:177]
	v_pk_fma_f32 v[122:123], v[122:123], v[120:121], v[178:179]
	ds_bpermute_b32 v180, v174, v166
	ds_bpermute_b32 v181, v174, v167
	ds_bpermute_b32 v182, v174, v124
	ds_bpermute_b32 v183, v174, v125
	s_waitcnt vmcnt(0) lgkmcnt(0)
	v_xor_b32_e32 v0, 0x80000000, v244
	v_xor_b32_e32 v184, 0x80000000, v245
	v_xor_b32_e32 v185, 0x80000000, v246
	v_xor_b32_e32 v186, 0x80000000, v247
	v_cndmask_b32_e64 v247, v247, v186, s[4:5]
	v_cndmask_b32_e64 v246, v246, v185, s[4:5]
	v_cndmask_b32_e64 v245, v245, v184, s[4:5]
	v_cndmask_b32_e64 v244, v244, v0, s[4:5]
	v_pk_mul_f32 v[244:245], v[244:245], v[180:181]
	v_pk_mul_f32 v[246:247], v[246:247], v[182:183]
	v_pk_fma_f32 v[166:167], v[166:167], v[240:241], v[244:245]
	v_pk_fma_f32 v[124:125], v[124:125], v[242:243], v[246:247]
.LBB0_260:
	s_or_b64 exec, exec, s[0:1]
	v_pk_mul_f32 v[176:177], v[116:117], v[116:117]
	v_pk_mul_f32 v[178:179], v[114:115], v[114:115]
	v_pk_mul_f32 v[184:185], v[104:105], v[104:105]
	v_pk_mov_b32 v[180:181], v[178:179], v[176:177] op_sel:[1,0]
	v_mov_b32_e32 v179, v177
	v_pk_add_f32 v[176:177], v[180:181], v[178:179]
	v_pk_mul_f32 v[178:179], v[112:113], v[112:113]
	v_pk_mul_f32 v[180:181], v[110:111], v[110:111]
	v_pk_add_f32 v[176:177], v[176:177], v[176:177] op_sel_hi:[0,1]
	v_pk_mov_b32 v[182:183], v[180:181], v[178:179] op_sel:[1,0]
	v_mov_b32_e32 v181, v179
	v_pk_add_f32 v[178:179], v[182:183], v[180:181]
	v_pk_mul_f32 v[180:181], v[108:109], v[108:109]
	v_pk_add_f32 v[178:179], v[178:179], v[178:179] op_sel_hi:[0,1]
	v_pk_mul_f32 v[182:183], v[106:107], v[106:107]
	v_pk_mul_f32 v[186:187], v[102:103], v[102:103]
	v_add_f32_e32 v183, v182, v183
	v_add_f32_e32 v181, v180, v181
	v_mov_b32_e32 v182, v186
	v_mov_b32_e32 v180, v187
	v_mov_b32_e32 v178, v184
	v_mov_b32_e32 v176, v185
	v_pk_add_f32 v[180:181], v[182:183], v[180:181]
	v_pk_add_f32 v[176:177], v[178:179], v[176:177]
	v_lshl_or_b32 v118, s2, 6, v148
	v_pk_add_f32 v[176:177], v[180:181], v[176:177]
	v_mov_b64_e32 v[120:121], s[12:13]
	v_add_f32_e32 v0, v176, v177
	v_mov_b32_e32 v178, v0
	v_mov_b32_e32 v248, v0
	s_nop 1
	v_permlane16_swap_b32_e32 v178, v248
	v_ashrrev_i32_e32 v119, 31, v118
	v_mad_i64_i32 v[120:121], s[0:1], v173, s80, v[120:121]
	v_lshl_add_u64 v[180:181], v[118:119], 1, v[120:121]
	s_waitcnt lgkmcnt(0)
	v_add_f32_e32 v0, v178, v248
	v_mov_b32_e32 v121, v0
	v_mov_b32_e32 v249, v0
	s_nop 1
	v_permlane32_swap_b32_e32 v121, v249
	v_cvt_pk_bf16_f32 v176, v132, v133
	v_cvt_pk_bf16_f32 v177, v130, v131
	v_cvt_pk_bf16_f32 v178, v128, v129
	v_cvt_pk_bf16_f32 v179, v126, v127
	s_waitcnt lgkmcnt(0)
; __device__ __forceinline__ unsigned cvt_pk_bf16(float lo, float hi) { unsigned r; asm volatile("v_cvt_pk_bf16_f32 %0, %1, %2" : "=v"(r) : "v"(lo), "v"(hi)); return r; }
;     __device__ __forceinline__ void operator()(const f32x4 (&acc)[2][2][4][2], const Unit& u, int wr, int wc, int fr, int fq) const {
;     ...
;                     ss += __shfl_xor(ss, 16); ss += __shfl_xor(ss, 32);
;                     const float rinv = 1.0f / sqrtf(ss * (1.0f / 64.0f) + LN_EPS);
; #pragma unroll
;                     for (int bj = 0; bj < 2; ++bj)
; #pragma unroll
;                         for (int n = 0; n < 2; ++n) x[bj][n] = x[bj][n] * rinv * gv[bj][n];
;                     if (w < SEQ) {
; #pragma unroll
;                         for (int bj = 0; bj < 2; ++bj) {
;                             const int pos = bj ? (w & 63) : (w >> 6);
; #pragma unroll
;                             for (int n = 0; n < 2; ++n) {
;                                 const f32x4 cs = *(const f32x4*)(tcos + pos * 16 + 8 * (fq & 1) + 4 * n);
;                                 const f32x4 sn = *(const f32x4*)(tsin + pos * 16 + 8 * (fq & 1) + 4 * n);
;                                 f32x4 p; p[0] = __shfl_xor(x[bj][n][0], 32); p[1] = __shfl_xor(x[bj][n][1], 32); p[2] = __shfl_xor(x[bj][n][2], 32); p[3] = __shfl_xor(x[bj][n][3], 32);
;                                 const f32x4 sgn = (fq < 2) ? -sn : sn;
;                                 x[bj][n] = x[bj][n] * cs + p * sgn;
;                             }
;                         }
;                     }
;                     bf16_t* rowp = O + (size_t)row * DIN + ocol;
; #pragma unroll
;                     for (int bj = 0; bj < 2; ++bj) { u32x4 wv; wv.x = cvt_pk_bf16(x[bj][0][0], x[bj][0][1]); wv.y = cvt_pk_bf16(x[bj][0][2], x[bj][0][3]); wv.z = cvt_pk_bf16(x[bj][1][0], x[bj][1][1]); wv.w = cvt_pk_bf16(x[bj][1][2], x[bj][1][3]);
;                         *(u32x4*)(rowp + 32 * bj) = wv; }
	v_add_f32_e32 v0, v121, v249
	v_fmamk_f32 v0, v0, 0x3c800000, v216
	v_mul_f32_e32 v121, 0x4f800000, v0
	v_cmp_gt_f32_e32 vcc, s69, v0
	flat_store_dwordx4 v[180:181], v[176:179]
	v_cvt_pk_bf16_f32 v120, v168, v169
	v_add_u32_e32 v127, 0xffffdf10, v173
	v_cndmask_b32_e32 v0, v0, v121, vcc
	v_sqrt_f32_e32 v126, v0
	v_cvt_pk_bf16_f32 v121, v122, v123
	v_cvt_pk_bf16_f32 v122, v166, v167
	v_cvt_pk_bf16_f32 v123, v124, v125
	flat_store_dwordx4 v[180:181], v[120:123] offset:64
	v_add_u32_e32 v124, -1, v126
	v_fma_f32 v125, -v124, v126, v0
	v_cmp_ge_f32_e64 s[0:1], 0, v125
	v_add_u32_e32 v125, 1, v126
	s_nop 0
	v_cndmask_b32_e64 v124, v126, v124, s[0:1]
	v_fma_f32 v126, -v125, v126, v0
	v_cmp_lt_f32_e64 s[0:1], 0, v126
	s_nop 1
	v_cndmask_b32_e64 v124, v124, v125, s[0:1]
	v_mul_f32_e32 v125, 0x37800000, v124
	v_cndmask_b32_e32 v124, v124, v125, vcc
	v_cmp_class_f32_e32 vcc, v0, v217
	s_nop 1
	v_cndmask_b32_e32 v0, v124, v0, vcc
	v_div_scale_f32 v125, s[0:1], v0, v0, 1.0
	v_rcp_f32_e32 v126, v125
	v_or_b32_e32 v124, 16, v173
	v_fma_f32 v120, -v125, v126, 1.0
	v_fmac_f32_e32 v126, v120, v126
	v_div_scale_f32 v120, vcc, 1.0, v0, 1.0
	v_mul_f32_e32 v121, v120, v126
	v_fma_f32 v122, -v125, v121, v120
	v_fmac_f32_e32 v121, v122, v126
	v_fma_f32 v120, -v125, v121, v120
	v_div_fmas_f32 v120, v120, v126, v121
	v_div_fixup_f32 v0, v120, v0, 1.0
	v_pk_mul_f32 v[120:121], v[114:115], v[0:1] op_sel_hi:[1,0]
	v_pk_mul_f32 v[114:115], v[116:117], v[0:1] op_sel_hi:[1,0]
	v_pk_mul_f32 v[116:117], v[164:165], v[120:121]
	v_pk_mul_f32 v[120:121], v[110:111], v[0:1] op_sel_hi:[1,0]
	v_cmp_lt_i32_e32 vcc, s67, v124
	v_pk_mul_f32 v[110:111], v[112:113], v[0:1] op_sel_hi:[1,0]
	v_pk_mul_f32 v[112:113], v[160:161], v[120:121]
	v_pk_mul_f32 v[120:121], v[106:107], v[0:1] op_sel_hi:[1,0]
	v_pk_mul_f32 v[106:107], v[108:109], v[0:1] op_sel_hi:[1,0]
	v_pk_mul_f32 v[102:103], v[102:103], v[0:1] op_sel_hi:[1,0]
	v_pk_mul_f32 v[104:105], v[104:105], v[0:1] op_sel_hi:[1,0]
	v_cndmask_b32_e32 v0, v124, v127, vcc
	v_pk_mul_f32 v[114:115], v[162:163], v[114:115]
	v_pk_mul_f32 v[110:111], v[158:159], v[110:111]
	v_pk_mul_f32 v[106:107], v[138:139], v[106:107]
	v_pk_mul_f32 v[120:121], v[140:141], v[120:121]
	v_pk_mul_f32 v[108:109], v[134:135], v[104:105]
	v_pk_mul_f32 v[122:123], v[136:137], v[102:103]
	v_cmp_gt_i32_e32 vcc, s66, v0
	s_and_saveexec_b64 s[0:1], vcc
	s_cbranch_execz .LBB0_262
	v_ashrrev_i32_e32 v102, 2, v0
	v_and_b32_e32 v102, -16, v102
	v_ashrrev_i32_e32 v103, 31, v102
	v_lshlrev_b64 v[102:103], 2, v[102:103]
	v_lshl_add_u64 v[130:131], v[150:151], 0, v[102:103]
	v_lshl_add_u64 v[132:133], v[152:153], 0, v[102:103]
	flat_load_dwordx4 v[102:105], v[130:131]
	flat_load_dwordx4 v[126:129], v[132:133]
	flat_load_dwordx4 v[240:243], v[130:131] offset:16
	flat_load_dwordx4 v[244:247], v[132:133] offset:16
	ds_bpermute_b32 v166, v174, v116
	ds_bpermute_b32 v167, v174, v117
	ds_bpermute_b32 v168, v174, v114
	ds_bpermute_b32 v169, v174, v115
	v_lshlrev_b32_e32 v0, 6, v0
	v_and_b32_e32 v0, 0x7c0, v0
	s_waitcnt vmcnt(0) lgkmcnt(0)
	v_xor_b32_e32 v125, 0x80000000, v126
	v_xor_b32_e32 v176, 0x80000000, v127
	v_xor_b32_e32 v177, 0x80000000, v128
	v_xor_b32_e32 v178, 0x80000000, v129
	v_cndmask_b32_e64 v129, v129, v178, s[4:5]
	v_cndmask_b32_e64 v128, v128, v177, s[4:5]
	v_cndmask_b32_e64 v127, v127, v176, s[4:5]
	v_cndmask_b32_e64 v126, v126, v125, s[4:5]
	v_pk_mul_f32 v[126:127], v[126:127], v[166:167]
	v_pk_mul_f32 v[128:129], v[128:129], v[168:169]
	v_pk_fma_f32 v[116:117], v[116:117], v[102:103], v[126:127]
	v_pk_fma_f32 v[114:115], v[114:115], v[104:105], v[128:129]
	ds_bpermute_b32 v130, v174, v112
	ds_bpermute_b32 v131, v174, v113
	ds_bpermute_b32 v132, v174, v110
	ds_bpermute_b32 v133, v174, v111
	ds_bpermute_b32 v169, v174, v107
	s_waitcnt vmcnt(0) lgkmcnt(0)
	v_xor_b32_e32 v125, 0x80000000, v244
	v_xor_b32_e32 v166, 0x80000000, v245
	v_xor_b32_e32 v167, 0x80000000, v246
	v_xor_b32_e32 v168, 0x80000000, v247
	v_cndmask_b32_e64 v247, v247, v168, s[4:5]
	v_cndmask_b32_e64 v246, v246, v167, s[4:5]
	v_cndmask_b32_e64 v245, v245, v166, s[4:5]
	v_cndmask_b32_e64 v244, v244, v125, s[4:5]
	v_pk_mul_f32 v[244:245], v[244:245], v[130:131]
	v_pk_mul_f32 v[246:247], v[246:247], v[132:133]
	v_lshl_add_u64 v[130:131], v[150:151], 0, v[0:1]
	v_pk_fma_f32 v[110:111], v[110:111], v[242:243], v[246:247]
	v_pk_fma_f32 v[112:113], v[112:113], v[240:241], v[244:245]
	v_lshl_add_u64 v[132:133], v[152:153], 0, v[0:1]
	flat_load_dwordx4 v[102:105], v[130:131]
	flat_load_dwordx4 v[126:129], v[132:133]
	flat_load_dwordx4 v[240:243], v[130:131] offset:16
	flat_load_dwordx4 v[244:247], v[132:133] offset:16
	ds_bpermute_b32 v166, v174, v120
	ds_bpermute_b32 v167, v174, v121
	ds_bpermute_b32 v168, v174, v106
	s_waitcnt vmcnt(0) lgkmcnt(0)
	v_xor_b32_e32 v0, 0x80000000, v126
	v_xor_b32_e32 v125, 0x80000000, v127
	v_xor_b32_e32 v176, 0x80000000, v128
	v_xor_b32_e32 v177, 0x80000000, v129
	v_cndmask_b32_e64 v129, v129, v177, s[4:5]
	v_cndmask_b32_e64 v128, v128, v176, s[4:5]
	v_cndmask_b32_e64 v127, v127, v125, s[4:5]
	v_cndmask_b32_e64 v126, v126, v0, s[4:5]
	v_pk_mul_f32 v[126:127], v[126:127], v[166:167]
	v_pk_mul_f32 v[128:129], v[128:129], v[168:169]
	v_pk_fma_f32 v[120:121], v[120:121], v[102:103], v[126:127]
	v_pk_fma_f32 v[106:107], v[106:107], v[104:105], v[128:129]
	ds_bpermute_b32 v130, v174, v122
	ds_bpermute_b32 v131, v174, v123
	ds_bpermute_b32 v132, v174, v108
	ds_bpermute_b32 v133, v174, v109
	s_waitcnt vmcnt(0) lgkmcnt(0)
	v_xor_b32_e32 v0, 0x80000000, v244
	v_xor_b32_e32 v125, 0x80000000, v245
	v_xor_b32_e32 v166, 0x80000000, v246
	v_xor_b32_e32 v167, 0x80000000, v247
	v_cndmask_b32_e64 v247, v247, v167, s[4:5]
	v_cndmask_b32_e64 v246, v246, v166, s[4:5]
	v_cndmask_b32_e64 v245, v245, v125, s[4:5]
	v_cndmask_b32_e64 v244, v244, v0, s[4:5]
	v_pk_mul_f32 v[244:245], v[244:245], v[130:131]
	v_pk_mul_f32 v[246:247], v[246:247], v[132:133]
	v_pk_fma_f32 v[122:123], v[122:123], v[240:241], v[244:245]
	v_pk_fma_f32 v[108:109], v[108:109], v[242:243], v[246:247]
; __device__ __forceinline__ unsigned cvt_pk_bf16(float lo, float hi) { unsigned r; asm volatile("v_cvt_pk_bf16_f32 %0, %1, %2" : "=v"(r) : "v"(lo), "v"(hi)); return r; }
;     __device__ __forceinline__ void operator()(const f32x4 (&acc)[2][2][4][2], const Unit& u, int wr, int wc, int fr, int fq) const {
;     ...
;                     f32x4 x[2][2]; float ss = 0.f;
; #pragma unroll
;                     for (int bj = 0; bj < 2; ++bj)
; #pragma unroll
;                         for (int n = 0; n < 2; ++n) { x[bj][n] = acc[ai][bj][m][n]; const f32x4 q = x[bj][n] * x[bj][n]; ss += (q[0] + q[1]) + (q[2] + q[3]); }
;                     ss += __shfl_xor(ss, 16); ss += __shfl_xor(ss, 32);
;                     const float rinv = 1.0f / sqrtf(ss * (1.0f / 64.0f) + LN_EPS);
; #pragma unroll
;                     for (int bj = 0; bj < 2; ++bj)
; #pragma unroll
;                         for (int n = 0; n < 2; ++n) x[bj][n] = x[bj][n] * rinv * gv[bj][n];
;                     if (w < SEQ) {
; #pragma unroll
;                         for (int bj = 0; bj < 2; ++bj) {
;                             const int pos = bj ? (w & 63) : (w >> 6);
; #pragma unroll
;                             for (int n = 0; n < 2; ++n) {
;                                 const f32x4 cs = *(const f32x4*)(tcos + pos * 16 + 8 * (fq & 1) + 4 * n);
;                                 const f32x4 sn = *(const f32x4*)(tsin + pos * 16 + 8 * (fq & 1) + 4 * n);
;                                 f32x4 p; p[0] = __shfl_xor(x[bj][n][0], 32); p[1] = __shfl_xor(x[bj][n][1], 32); p[2] = __shfl_xor(x[bj][n][2], 32); p[3] = __shfl_xor(x[bj][n][3], 32);
;                                 const f32x4 sgn = (fq < 2) ? -sn : sn;
;                                 x[bj][n] = x[bj][n] * cs + p * sgn;
;                             }
;                         }
;                     }
;                     bf16_t* rowp = O + (size_t)row * DIN + ocol;
; #pragma unroll
;                     for (int bj = 0; bj < 2; ++bj) { u32x4 wv; wv.x = cvt_pk_bf16(x[bj][0][0], x[bj][0][1]); wv.y = cvt_pk_bf16(x[bj][0][2], x[bj][0][3]); wv.z = cvt_pk_bf16(x[bj][1][0], x[bj][1][1]); wv.w = cvt_pk_bf16(x[bj][1][2], x[bj][1][3]);
;                         *(u32x4*)(rowp + 32 * bj) = wv; }
.LBB0_262:
	s_or_b64 exec, exec, s[0:1]
	v_pk_mul_f32 v[104:105], v[100:101], v[100:101]
	v_pk_mul_f32 v[126:127], v[98:99], v[98:99]
	v_pk_mul_f32 v[132:133], v[88:89], v[88:89]
	v_pk_mov_b32 v[128:129], v[126:127], v[104:105] op_sel:[1,0]
	v_mov_b32_e32 v127, v105
	v_pk_add_f32 v[104:105], v[128:129], v[126:127]
	v_pk_mul_f32 v[126:127], v[96:97], v[96:97]
	v_pk_mul_f32 v[128:129], v[94:95], v[94:95]
	v_pk_add_f32 v[104:105], v[104:105], v[104:105] op_sel_hi:[0,1]
	v_pk_mov_b32 v[130:131], v[128:129], v[126:127] op_sel:[1,0]
	v_mov_b32_e32 v129, v127
	v_pk_add_f32 v[126:127], v[130:131], v[128:129]
	v_pk_mul_f32 v[128:129], v[92:93], v[92:93]
	v_pk_add_f32 v[126:127], v[126:127], v[126:127] op_sel_hi:[0,1]
	v_pk_mul_f32 v[130:131], v[90:91], v[90:91]
	v_pk_mul_f32 v[166:167], v[86:87], v[86:87]
	v_add_f32_e32 v131, v130, v131
	v_add_f32_e32 v129, v128, v129
	v_mov_b32_e32 v130, v166
	v_mov_b32_e32 v128, v167
	v_mov_b32_e32 v126, v132
	v_mov_b32_e32 v104, v133
	v_pk_add_f32 v[128:129], v[130:131], v[128:129]
	v_pk_add_f32 v[104:105], v[126:127], v[104:105]
	v_mov_b64_e32 v[102:103], s[12:13]
	v_pk_add_f32 v[104:105], v[128:129], v[104:105]
	v_mad_i64_i32 v[102:103], s[0:1], v124, s80, v[102:103]
	v_add_f32_e32 v0, v104, v105
	v_mov_b32_e32 v104, v0
	v_mov_b32_e32 v248, v0
	s_nop 1
	v_permlane16_swap_b32_e32 v104, v248
	v_lshl_add_u64 v[124:125], v[118:119], 1, v[102:103]
	v_cvt_pk_bf16_f32 v102, v116, v117
	v_cvt_pk_bf16_f32 v103, v114, v115
	s_waitcnt lgkmcnt(0)
	v_add_f32_e32 v0, v104, v248
	v_mov_b32_e32 v114, v0
	v_mov_b32_e32 v249, v0
	s_nop 1
	v_permlane32_swap_b32_e32 v114, v249
	v_cvt_pk_bf16_f32 v104, v112, v113
	v_cvt_pk_bf16_f32 v105, v110, v111
	flat_store_dwordx4 v[124:125], v[102:105]
	s_waitcnt lgkmcnt(0)
	v_add_f32_e32 v0, v114, v249
	v_fmamk_f32 v0, v0, 0x3c800000, v216
	v_mul_f32_e32 v103, 0x4f800000, v0
	v_cmp_gt_f32_e32 vcc, s69, v0
	v_cvt_pk_bf16_f32 v102, v120, v121
	s_nop 1
	v_cndmask_b32_e32 v0, v0, v103, vcc
	v_sqrt_f32_e32 v110, v0
	v_cvt_pk_bf16_f32 v103, v106, v107
	v_cvt_pk_bf16_f32 v104, v122, v123
	v_cvt_pk_bf16_f32 v105, v108, v109
	flat_store_dwordx4 v[124:125], v[102:105] offset:64
	v_add_u32_e32 v106, -1, v110
	v_fma_f32 v107, -v106, v110, v0
	v_cmp_ge_f32_e64 s[0:1], 0, v107
	v_add_u32_e32 v107, 1, v110
	v_fma_f32 v108, -v107, v110, v0
	v_cndmask_b32_e64 v106, v110, v106, s[0:1]
	v_cmp_lt_f32_e64 s[0:1], 0, v108
	v_add_u32_e32 v109, 0xffffdf20, v173
	s_nop 0
	v_cndmask_b32_e64 v106, v106, v107, s[0:1]
	v_mul_f32_e32 v107, 0x37800000, v106
	v_cndmask_b32_e32 v106, v106, v107, vcc
	v_cmp_class_f32_e32 vcc, v0, v217
	s_nop 1
	v_cndmask_b32_e32 v0, v106, v0, vcc
	v_div_scale_f32 v107, s[0:1], v0, v0, 1.0
	v_rcp_f32_e32 v108, v107
	v_or_b32_e32 v106, 32, v173
	v_fma_f32 v102, -v107, v108, 1.0
	v_fmac_f32_e32 v108, v102, v108
	v_div_scale_f32 v102, vcc, 1.0, v0, 1.0
	v_mul_f32_e32 v103, v102, v108
	v_fma_f32 v104, -v107, v103, v102
	v_fmac_f32_e32 v103, v104, v108
	v_fma_f32 v102, -v107, v103, v102
	v_div_fmas_f32 v102, v102, v108, v103
	v_div_fixup_f32 v0, v102, v0, 1.0
	v_pk_mul_f32 v[102:103], v[98:99], v[0:1] op_sel_hi:[1,0]
	v_pk_mul_f32 v[98:99], v[100:101], v[0:1] op_sel_hi:[1,0]
	v_pk_mul_f32 v[100:101], v[164:165], v[102:103]
	v_pk_mul_f32 v[102:103], v[94:95], v[0:1] op_sel_hi:[1,0]
	v_cmp_lt_i32_e32 vcc, s67, v106
	v_pk_mul_f32 v[94:95], v[96:97], v[0:1] op_sel_hi:[1,0]
	v_pk_mul_f32 v[96:97], v[160:161], v[102:103]
	v_pk_mul_f32 v[102:103], v[90:91], v[0:1] op_sel_hi:[1,0]
	v_pk_mul_f32 v[90:91], v[92:93], v[0:1] op_sel_hi:[1,0]
	v_pk_mul_f32 v[86:87], v[86:87], v[0:1] op_sel_hi:[1,0]
	v_pk_mul_f32 v[88:89], v[88:89], v[0:1] op_sel_hi:[1,0]
	v_cndmask_b32_e32 v0, v106, v109, vcc
	v_pk_mul_f32 v[98:99], v[162:163], v[98:99]
	v_pk_mul_f32 v[94:95], v[158:159], v[94:95]
	v_pk_mul_f32 v[90:91], v[138:139], v[90:91]
	v_pk_mul_f32 v[104:105], v[140:141], v[102:103]
	v_pk_mul_f32 v[92:93], v[134:135], v[88:89]
	v_pk_mul_f32 v[102:103], v[136:137], v[86:87]
	v_cmp_gt_i32_e32 vcc, s66, v0
	s_and_saveexec_b64 s[0:1], vcc
	s_cbranch_execz .LBB0_264
	v_ashrrev_i32_e32 v86, 2, v0
	v_and_b32_e32 v86, -16, v86
	v_ashrrev_i32_e32 v87, 31, v86
	v_lshlrev_b64 v[86:87], 2, v[86:87]
	v_lshl_add_u64 v[112:113], v[150:151], 0, v[86:87]
	v_lshl_add_u64 v[114:115], v[152:153], 0, v[86:87]
	flat_load_dwordx4 v[86:89], v[112:113]
	flat_load_dwordx4 v[108:111], v[114:115]
	flat_load_dwordx4 v[240:243], v[112:113] offset:16
	flat_load_dwordx4 v[244:247], v[114:115] offset:16
	ds_bpermute_b32 v116, v174, v100
	ds_bpermute_b32 v117, v174, v101
	ds_bpermute_b32 v120, v174, v98
	ds_bpermute_b32 v121, v174, v99
	v_lshlrev_b32_e32 v0, 6, v0
	v_and_b32_e32 v0, 0xbc0, v0
	s_waitcnt vmcnt(0) lgkmcnt(0)
	v_xor_b32_e32 v107, 0x80000000, v108
	v_xor_b32_e32 v122, 0x80000000, v109
	v_xor_b32_e32 v123, 0x80000000, v110
	v_xor_b32_e32 v124, 0x80000000, v111
	v_cndmask_b32_e64 v111, v111, v124, s[4:5]
	v_cndmask_b32_e64 v110, v110, v123, s[4:5]
	v_cndmask_b32_e64 v109, v109, v122, s[4:5]
	v_cndmask_b32_e64 v108, v108, v107, s[4:5]
	v_pk_mul_f32 v[108:109], v[108:109], v[116:117]
	v_pk_mul_f32 v[110:111], v[110:111], v[120:121]
	v_pk_fma_f32 v[100:101], v[100:101], v[86:87], v[108:109]
	v_pk_fma_f32 v[98:99], v[98:99], v[88:89], v[110:111]
	ds_bpermute_b32 v112, v174, v96
	ds_bpermute_b32 v113, v174, v97
	ds_bpermute_b32 v114, v174, v94
	ds_bpermute_b32 v115, v174, v95
	ds_bpermute_b32 v121, v174, v91
	s_waitcnt vmcnt(0) lgkmcnt(0)
; __device__ __forceinline__ unsigned cvt_pk_bf16(float lo, float hi) { unsigned r; asm volatile("v_cvt_pk_bf16_f32 %0, %1, %2" : "=v"(r) : "v"(lo), "v"(hi)); return r; }
;     __device__ __forceinline__ void operator()(const f32x4 (&acc)[2][2][4][2], const Unit& u, int wr, int wc, int fr, int fq) const {
;     ...
;                     f32x4 x[2][2]; float ss = 0.f;
; #pragma unroll
;                     for (int bj = 0; bj < 2; ++bj)
; #pragma unroll
;                         for (int n = 0; n < 2; ++n) { x[bj][n] = acc[ai][bj][m][n]; const f32x4 q = x[bj][n] * x[bj][n]; ss += (q[0] + q[1]) + (q[2] + q[3]); }
;                     ss += __shfl_xor(ss, 16); ss += __shfl_xor(ss, 32);
;                     const float rinv = 1.0f / sqrtf(ss * (1.0f / 64.0f) + LN_EPS);
; #pragma unroll
;                     for (int bj = 0; bj < 2; ++bj)
; #pragma unroll
;                         for (int n = 0; n < 2; ++n) x[bj][n] = x[bj][n] * rinv * gv[bj][n];
;                     if (w < SEQ) {
; #pragma unroll
;                         for (int bj = 0; bj < 2; ++bj) {
;                             const int pos = bj ? (w & 63) : (w >> 6);
; #pragma unroll
;                             for (int n = 0; n < 2; ++n) {
;                                 const f32x4 cs = *(const f32x4*)(tcos + pos * 16 + 8 * (fq & 1) + 4 * n);
;                                 const f32x4 sn = *(const f32x4*)(tsin + pos * 16 + 8 * (fq & 1) + 4 * n);
;                                 f32x4 p; p[0] = __shfl_xor(x[bj][n][0], 32); p[1] = __shfl_xor(x[bj][n][1], 32); p[2] = __shfl_xor(x[bj][n][2], 32); p[3] = __shfl_xor(x[bj][n][3], 32);
;                                 const f32x4 sgn = (fq < 2) ? -sn : sn;
;                                 x[bj][n] = x[bj][n] * cs + p * sgn;
;                             }
;                         }
;                     }
;                     bf16_t* rowp = O + (size_t)row * DIN + ocol;
; #pragma unroll
;                     for (int bj = 0; bj < 2; ++bj) { u32x4 wv; wv.x = cvt_pk_bf16(x[bj][0][0], x[bj][0][1]); wv.y = cvt_pk_bf16(x[bj][0][2], x[bj][0][3]); wv.z = cvt_pk_bf16(x[bj][1][0], x[bj][1][1]); wv.w = cvt_pk_bf16(x[bj][1][2], x[bj][1][3]);
;                         *(u32x4*)(rowp + 32 * bj) = wv; }
	v_xor_b32_e32 v107, 0x80000000, v244
	v_xor_b32_e32 v116, 0x80000000, v245
	v_xor_b32_e32 v117, 0x80000000, v246
	v_xor_b32_e32 v120, 0x80000000, v247
	v_cndmask_b32_e64 v247, v247, v120, s[4:5]
	v_cndmask_b32_e64 v246, v246, v117, s[4:5]
	v_cndmask_b32_e64 v245, v245, v116, s[4:5]
	v_cndmask_b32_e64 v244, v244, v107, s[4:5]
	v_pk_mul_f32 v[244:245], v[244:245], v[112:113]
	v_pk_mul_f32 v[246:247], v[246:247], v[114:115]
	v_lshl_add_u64 v[112:113], v[150:151], 0, v[0:1]
	v_pk_fma_f32 v[94:95], v[94:95], v[242:243], v[246:247]
	v_pk_fma_f32 v[96:97], v[96:97], v[240:241], v[244:245]
	v_lshl_add_u64 v[114:115], v[152:153], 0, v[0:1]
	flat_load_dwordx4 v[86:89], v[112:113]
	flat_load_dwordx4 v[108:111], v[114:115]
	flat_load_dwordx4 v[240:243], v[112:113] offset:16
	flat_load_dwordx4 v[244:247], v[114:115] offset:16
	ds_bpermute_b32 v116, v174, v104
	ds_bpermute_b32 v117, v174, v105
	ds_bpermute_b32 v120, v174, v90
	s_waitcnt vmcnt(0) lgkmcnt(0)
	v_xor_b32_e32 v0, 0x80000000, v108
	v_xor_b32_e32 v107, 0x80000000, v109
	v_xor_b32_e32 v122, 0x80000000, v110
	v_xor_b32_e32 v123, 0x80000000, v111
	v_cndmask_b32_e64 v111, v111, v123, s[4:5]
	v_cndmask_b32_e64 v110, v110, v122, s[4:5]
	v_cndmask_b32_e64 v109, v109, v107, s[4:5]
	v_cndmask_b32_e64 v108, v108, v0, s[4:5]
	v_pk_mul_f32 v[108:109], v[108:109], v[116:117]
	v_pk_mul_f32 v[110:111], v[110:111], v[120:121]
	v_pk_fma_f32 v[104:105], v[104:105], v[86:87], v[108:109]
	v_pk_fma_f32 v[90:91], v[90:91], v[88:89], v[110:111]
	ds_bpermute_b32 v112, v174, v102
	ds_bpermute_b32 v113, v174, v103
	ds_bpermute_b32 v114, v174, v92
	ds_bpermute_b32 v115, v174, v93
	s_waitcnt vmcnt(0) lgkmcnt(0)
	v_xor_b32_e32 v0, 0x80000000, v244
	v_xor_b32_e32 v107, 0x80000000, v245
	v_xor_b32_e32 v116, 0x80000000, v246
	v_xor_b32_e32 v117, 0x80000000, v247
	v_cndmask_b32_e64 v247, v247, v117, s[4:5]
	v_cndmask_b32_e64 v246, v246, v116, s[4:5]
	v_cndmask_b32_e64 v245, v245, v107, s[4:5]
	v_cndmask_b32_e64 v244, v244, v0, s[4:5]
	v_pk_mul_f32 v[244:245], v[244:245], v[112:113]
	v_pk_mul_f32 v[246:247], v[246:247], v[114:115]
	v_pk_fma_f32 v[102:103], v[102:103], v[240:241], v[244:245]
	v_pk_fma_f32 v[92:93], v[92:93], v[242:243], v[246:247]
.LBB0_264:
	s_or_b64 exec, exec, s[0:1]
	v_pk_mul_f32 v[88:89], v[84:85], v[84:85]
	v_pk_mul_f32 v[108:109], v[82:83], v[82:83]
	v_pk_mul_f32 v[114:115], v[72:73], v[72:73]
	v_pk_mov_b32 v[110:111], v[108:109], v[88:89] op_sel:[1,0]
	v_mov_b32_e32 v109, v89
	v_pk_add_f32 v[88:89], v[110:111], v[108:109]
	v_pk_mul_f32 v[108:109], v[80:81], v[80:81]
	v_pk_mul_f32 v[110:111], v[78:79], v[78:79]
	v_pk_add_f32 v[88:89], v[88:89], v[88:89] op_sel_hi:[0,1]
	v_pk_mov_b32 v[112:113], v[110:111], v[108:109] op_sel:[1,0]
	v_mov_b32_e32 v111, v109
	v_pk_add_f32 v[108:109], v[112:113], v[110:111]
	v_pk_mul_f32 v[110:111], v[76:77], v[76:77]
	v_pk_add_f32 v[108:109], v[108:109], v[108:109] op_sel_hi:[0,1]
	v_pk_mul_f32 v[112:113], v[74:75], v[74:75]
	v_pk_mul_f32 v[116:117], v[70:71], v[70:71]
	v_add_f32_e32 v113, v112, v113
	v_add_f32_e32 v111, v110, v111
	v_mov_b32_e32 v112, v116
	v_mov_b32_e32 v110, v117
	v_mov_b32_e32 v108, v114
	v_mov_b32_e32 v88, v115
	v_pk_add_f32 v[110:111], v[112:113], v[110:111]
	v_pk_add_f32 v[88:89], v[108:109], v[88:89]
	v_mov_b64_e32 v[86:87], s[12:13]
	v_pk_add_f32 v[88:89], v[110:111], v[88:89]
	v_mad_i64_i32 v[86:87], s[0:1], v106, s80, v[86:87]
	v_add_f32_e32 v0, v88, v89
	v_mov_b32_e32 v88, v0
	v_mov_b32_e32 v248, v0
	s_nop 1
	v_permlane16_swap_b32_e32 v88, v248
	v_lshl_add_u64 v[106:107], v[118:119], 1, v[86:87]
	v_cvt_pk_bf16_f32 v86, v100, v101
	v_cvt_pk_bf16_f32 v87, v98, v99
	s_waitcnt lgkmcnt(0)
	v_add_f32_e32 v0, v88, v248
	v_mov_b32_e32 v98, v0
	v_mov_b32_e32 v249, v0
	s_nop 1
	v_permlane32_swap_b32_e32 v98, v249
	v_cvt_pk_bf16_f32 v88, v96, v97
	v_cvt_pk_bf16_f32 v89, v94, v95
	flat_store_dwordx4 v[106:107], v[86:89]
	s_waitcnt lgkmcnt(0)
	v_add_f32_e32 v0, v98, v249
	v_fmamk_f32 v0, v0, 0x3c800000, v216
	v_mul_f32_e32 v87, 0x4f800000, v0
	v_cmp_gt_f32_e32 vcc, s69, v0
	v_cvt_pk_bf16_f32 v86, v104, v105
	s_nop 1
	v_cndmask_b32_e32 v0, v0, v87, vcc
	v_sqrt_f32_e32 v94, v0
	v_cvt_pk_bf16_f32 v87, v90, v91
	v_cvt_pk_bf16_f32 v88, v102, v103
	v_cvt_pk_bf16_f32 v89, v92, v93
	flat_store_dwordx4 v[106:107], v[86:89] offset:64
	v_add_u32_e32 v90, -1, v94
	v_fma_f32 v91, -v90, v94, v0
	v_cmp_ge_f32_e64 s[0:1], 0, v91
	v_add_u32_e32 v91, 1, v94
	v_fma_f32 v92, -v91, v94, v0
	v_cndmask_b32_e64 v90, v94, v90, s[0:1]
	v_cmp_lt_f32_e64 s[0:1], 0, v92
	v_add_u32_e32 v93, 0xffffdf30, v173
	s_nop 0
	v_cndmask_b32_e64 v90, v90, v91, s[0:1]
	v_mul_f32_e32 v91, 0x37800000, v90
	v_cndmask_b32_e32 v90, v90, v91, vcc
	v_cmp_class_f32_e32 vcc, v0, v217
	s_nop 1
	v_cndmask_b32_e32 v0, v90, v0, vcc
	v_div_scale_f32 v91, s[0:1], v0, v0, 1.0
	v_rcp_f32_e32 v92, v91
	v_or_b32_e32 v90, 48, v173
	v_fma_f32 v86, -v91, v92, 1.0
	v_fmac_f32_e32 v92, v86, v92
	v_div_scale_f32 v86, vcc, 1.0, v0, 1.0
	v_mul_f32_e32 v87, v86, v92
	v_fma_f32 v88, -v91, v87, v86
	v_fmac_f32_e32 v87, v88, v92
	v_fma_f32 v86, -v91, v87, v86
	v_div_fmas_f32 v86, v86, v92, v87
	v_div_fixup_f32 v0, v86, v0, 1.0
	v_pk_mul_f32 v[86:87], v[82:83], v[0:1] op_sel_hi:[1,0]
	v_pk_mul_f32 v[82:83], v[84:85], v[0:1] op_sel_hi:[1,0]
	v_pk_mul_f32 v[84:85], v[164:165], v[86:87]
	v_pk_mul_f32 v[86:87], v[78:79], v[0:1] op_sel_hi:[1,0]
	v_cmp_lt_i32_e32 vcc, s67, v90
	v_pk_mul_f32 v[78:79], v[80:81], v[0:1] op_sel_hi:[1,0]
	v_pk_mul_f32 v[80:81], v[160:161], v[86:87]
	v_pk_mul_f32 v[86:87], v[74:75], v[0:1] op_sel_hi:[1,0]
	v_pk_mul_f32 v[74:75], v[76:77], v[0:1] op_sel_hi:[1,0]
	v_pk_mul_f32 v[70:71], v[70:71], v[0:1] op_sel_hi:[1,0]
	v_pk_mul_f32 v[72:73], v[72:73], v[0:1] op_sel_hi:[1,0]
	v_cndmask_b32_e32 v0, v90, v93, vcc
	v_pk_mul_f32 v[82:83], v[162:163], v[82:83]
	v_pk_mul_f32 v[78:79], v[158:159], v[78:79]
	v_pk_mul_f32 v[74:75], v[138:139], v[74:75]
	v_pk_mul_f32 v[86:87], v[140:141], v[86:87]
	v_pk_mul_f32 v[76:77], v[134:135], v[72:73]
	v_pk_mul_f32 v[88:89], v[136:137], v[70:71]
	v_cmp_gt_i32_e32 vcc, s66, v0
	s_and_saveexec_b64 s[0:1], vcc
	s_cbranch_execz .LBB0_266
; __device__ __forceinline__ unsigned cvt_pk_bf16(float lo, float hi) { unsigned r; asm volatile("v_cvt_pk_bf16_f32 %0, %1, %2" : "=v"(r) : "v"(lo), "v"(hi)); return r; }
;     __device__ __forceinline__ void operator()(const f32x4 (&acc)[2][2][4][2], const Unit& u, int wr, int wc, int fr, int fq) const {
;     ...
;                     f32x4 x[2][2]; float ss = 0.f;
; #pragma unroll
;                     for (int bj = 0; bj < 2; ++bj)
; #pragma unroll
;                         for (int n = 0; n < 2; ++n) { x[bj][n] = acc[ai][bj][m][n]; const f32x4 q = x[bj][n] * x[bj][n]; ss += (q[0] + q[1]) + (q[2] + q[3]); }
;                     ss += __shfl_xor(ss, 16); ss += __shfl_xor(ss, 32);
;                     const float rinv = 1.0f / sqrtf(ss * (1.0f / 64.0f) + LN_EPS);
; #pragma unroll
;                     for (int bj = 0; bj < 2; ++bj)
; #pragma unroll
;                         for (int n = 0; n < 2; ++n) x[bj][n] = x[bj][n] * rinv * gv[bj][n];
;                     if (w < SEQ) {
; #pragma unroll
;                         for (int bj = 0; bj < 2; ++bj) {
;                             const int pos = bj ? (w & 63) : (w >> 6);
; #pragma unroll
;                             for (int n = 0; n < 2; ++n) {
;                                 const f32x4 cs = *(const f32x4*)(tcos + pos * 16 + 8 * (fq & 1) + 4 * n);
;                                 const f32x4 sn = *(const f32x4*)(tsin + pos * 16 + 8 * (fq & 1) + 4 * n);
;                                 f32x4 p; p[0] = __shfl_xor(x[bj][n][0], 32); p[1] = __shfl_xor(x[bj][n][1], 32); p[2] = __shfl_xor(x[bj][n][2], 32); p[3] = __shfl_xor(x[bj][n][3], 32);
;                                 const f32x4 sgn = (fq < 2) ? -sn : sn;
;                                 x[bj][n] = x[bj][n] * cs + p * sgn;
;                             }
;                         }
;                     }
;                     bf16_t* rowp = O + (size_t)row * DIN + ocol;
; #pragma unroll
;                     for (int bj = 0; bj < 2; ++bj) { u32x4 wv; wv.x = cvt_pk_bf16(x[bj][0][0], x[bj][0][1]); wv.y = cvt_pk_bf16(x[bj][0][2], x[bj][0][3]); wv.z = cvt_pk_bf16(x[bj][1][0], x[bj][1][1]); wv.w = cvt_pk_bf16(x[bj][1][2], x[bj][1][3]);
;                         *(u32x4*)(rowp + 32 * bj) = wv; }
	v_ashrrev_i32_e32 v70, 2, v0
	v_and_b32_e32 v70, -16, v70
	v_ashrrev_i32_e32 v71, 31, v70
	v_lshlrev_b64 v[70:71], 2, v[70:71]
	v_lshl_add_u64 v[96:97], v[150:151], 0, v[70:71]
	v_lshl_add_u64 v[98:99], v[152:153], 0, v[70:71]
	flat_load_dwordx4 v[70:73], v[96:97]
	flat_load_dwordx4 v[92:95], v[98:99]
	flat_load_dwordx4 v[240:243], v[96:97] offset:16
	flat_load_dwordx4 v[244:247], v[98:99] offset:16
	ds_bpermute_b32 v100, v174, v84
	ds_bpermute_b32 v101, v174, v85
	ds_bpermute_b32 v102, v174, v82
	ds_bpermute_b32 v103, v174, v83
	v_lshlrev_b32_e32 v0, 6, v0
	v_and_b32_e32 v0, 0xfc0, v0
	s_waitcnt vmcnt(0) lgkmcnt(0)
	v_xor_b32_e32 v91, 0x80000000, v92
	v_xor_b32_e32 v104, 0x80000000, v93
	v_xor_b32_e32 v105, 0x80000000, v94
	v_xor_b32_e32 v106, 0x80000000, v95
	v_cndmask_b32_e64 v95, v95, v106, s[4:5]
	v_cndmask_b32_e64 v94, v94, v105, s[4:5]
	v_cndmask_b32_e64 v93, v93, v104, s[4:5]
	v_cndmask_b32_e64 v92, v92, v91, s[4:5]
	v_pk_mul_f32 v[92:93], v[92:93], v[100:101]
	v_pk_mul_f32 v[94:95], v[94:95], v[102:103]
	v_pk_fma_f32 v[84:85], v[84:85], v[70:71], v[92:93]
	v_pk_fma_f32 v[82:83], v[82:83], v[72:73], v[94:95]
	ds_bpermute_b32 v96, v174, v80
	ds_bpermute_b32 v97, v174, v81
	ds_bpermute_b32 v98, v174, v78
	ds_bpermute_b32 v99, v174, v79
	ds_bpermute_b32 v103, v174, v75
	s_waitcnt vmcnt(0) lgkmcnt(0)
	v_xor_b32_e32 v91, 0x80000000, v244
	v_xor_b32_e32 v100, 0x80000000, v245
	v_xor_b32_e32 v101, 0x80000000, v246
	v_xor_b32_e32 v102, 0x80000000, v247
	v_cndmask_b32_e64 v247, v247, v102, s[4:5]
	v_cndmask_b32_e64 v246, v246, v101, s[4:5]
	v_cndmask_b32_e64 v245, v245, v100, s[4:5]
	v_cndmask_b32_e64 v244, v244, v91, s[4:5]
	v_pk_mul_f32 v[244:245], v[244:245], v[96:97]
	v_pk_mul_f32 v[246:247], v[246:247], v[98:99]
	v_lshl_add_u64 v[96:97], v[150:151], 0, v[0:1]
	v_pk_fma_f32 v[78:79], v[78:79], v[242:243], v[246:247]
	v_pk_fma_f32 v[80:81], v[80:81], v[240:241], v[244:245]
	v_lshl_add_u64 v[98:99], v[152:153], 0, v[0:1]
	flat_load_dwordx4 v[70:73], v[96:97]
	flat_load_dwordx4 v[92:95], v[98:99]
	flat_load_dwordx4 v[240:243], v[96:97] offset:16
	flat_load_dwordx4 v[244:247], v[98:99] offset:16
	ds_bpermute_b32 v100, v174, v86
	ds_bpermute_b32 v101, v174, v87
	ds_bpermute_b32 v102, v174, v74
	s_waitcnt vmcnt(0) lgkmcnt(0)
	v_xor_b32_e32 v0, 0x80000000, v92
	v_xor_b32_e32 v91, 0x80000000, v93
	v_xor_b32_e32 v104, 0x80000000, v94
	v_xor_b32_e32 v105, 0x80000000, v95
	v_cndmask_b32_e64 v95, v95, v105, s[4:5]
	v_cndmask_b32_e64 v94, v94, v104, s[4:5]
	v_cndmask_b32_e64 v93, v93, v91, s[4:5]
	v_cndmask_b32_e64 v92, v92, v0, s[4:5]
	v_pk_mul_f32 v[92:93], v[92:93], v[100:101]
	v_pk_mul_f32 v[94:95], v[94:95], v[102:103]
	v_pk_fma_f32 v[86:87], v[86:87], v[70:71], v[92:93]
	v_pk_fma_f32 v[74:75], v[74:75], v[72:73], v[94:95]
	ds_bpermute_b32 v96, v174, v88
	ds_bpermute_b32 v97, v174, v89
	ds_bpermute_b32 v98, v174, v76
	ds_bpermute_b32 v99, v174, v77
	s_waitcnt vmcnt(0) lgkmcnt(0)
	v_xor_b32_e32 v0, 0x80000000, v244
	v_xor_b32_e32 v91, 0x80000000, v245
	v_xor_b32_e32 v100, 0x80000000, v246
	v_xor_b32_e32 v101, 0x80000000, v247
	v_cndmask_b32_e64 v247, v247, v101, s[4:5]
	v_cndmask_b32_e64 v246, v246, v100, s[4:5]
	v_cndmask_b32_e64 v245, v245, v91, s[4:5]
	v_cndmask_b32_e64 v244, v244, v0, s[4:5]
	v_pk_mul_f32 v[244:245], v[244:245], v[96:97]
	v_pk_mul_f32 v[246:247], v[246:247], v[98:99]
	v_pk_fma_f32 v[88:89], v[88:89], v[240:241], v[244:245]
	v_pk_fma_f32 v[76:77], v[76:77], v[242:243], v[246:247]
.LBB0_266:
	s_or_b64 exec, exec, s[0:1]
	v_pk_mul_f32 v[72:73], v[68:69], v[68:69]
	v_pk_mul_f32 v[92:93], v[66:67], v[66:67]
	v_pk_mul_f32 v[98:99], v[56:57], v[56:57]
	v_pk_mov_b32 v[94:95], v[92:93], v[72:73] op_sel:[1,0]
	v_mov_b32_e32 v93, v73
	v_pk_add_f32 v[72:73], v[94:95], v[92:93]
	v_pk_mul_f32 v[92:93], v[64:65], v[64:65]
	v_pk_mul_f32 v[94:95], v[62:63], v[62:63]
	v_pk_add_f32 v[72:73], v[72:73], v[72:73] op_sel_hi:[0,1]
	v_pk_mov_b32 v[96:97], v[94:95], v[92:93] op_sel:[1,0]
	v_mov_b32_e32 v95, v93
	v_pk_add_f32 v[92:93], v[96:97], v[94:95]
	v_pk_mul_f32 v[94:95], v[60:61], v[60:61]
	v_pk_add_f32 v[92:93], v[92:93], v[92:93] op_sel_hi:[0,1]
	v_pk_mul_f32 v[96:97], v[58:59], v[58:59]
	v_pk_mul_f32 v[100:101], v[54:55], v[54:55]
	v_add_f32_e32 v97, v96, v97
	v_add_f32_e32 v95, v94, v95
	v_mov_b32_e32 v96, v100
	v_mov_b32_e32 v94, v101
	v_mov_b32_e32 v92, v98
	v_mov_b32_e32 v72, v99
	v_pk_add_f32 v[94:95], v[96:97], v[94:95]
	v_pk_add_f32 v[72:73], v[92:93], v[72:73]
	v_mov_b64_e32 v[70:71], s[12:13]
	v_pk_add_f32 v[72:73], v[94:95], v[72:73]
	v_mad_i64_i32 v[70:71], s[0:1], v90, s80, v[70:71]
	v_add_f32_e32 v0, v72, v73
	v_mov_b32_e32 v72, v0
	v_mov_b32_e32 v248, v0
	s_nop 1
	v_permlane16_swap_b32_e32 v72, v248
	v_lshl_add_u64 v[90:91], v[118:119], 1, v[70:71]
	v_cvt_pk_bf16_f32 v70, v84, v85
	v_cvt_pk_bf16_f32 v71, v82, v83
	s_waitcnt lgkmcnt(0)
	v_add_f32_e32 v0, v72, v248
	v_mov_b32_e32 v82, v0
	v_mov_b32_e32 v249, v0
	s_nop 1
	v_permlane32_swap_b32_e32 v82, v249
	v_cvt_pk_bf16_f32 v72, v80, v81
	v_cvt_pk_bf16_f32 v73, v78, v79
	flat_store_dwordx4 v[90:91], v[70:73]
	s_waitcnt lgkmcnt(0)
;     __device__ __forceinline__ void operator()(const f32x4 (&acc)[2][2][4][2], const Unit& u, int wr, int wc, int fr, int fq) const {
;     ...
;                     ss += __shfl_xor(ss, 16); ss += __shfl_xor(ss, 32);
;                     const float rinv = 1.0f / sqrtf(ss * (1.0f / 64.0f) + LN_EPS);
; #pragma unroll
;                     for (int bj = 0; bj < 2; ++bj)
; #pragma unroll
;                         for (int n = 0; n < 2; ++n) x[bj][n] = x[bj][n] * rinv * gv[bj][n];
;                     if (w < SEQ) {
; #pragma unroll
;                         for (int bj = 0; bj < 2; ++bj) {
;                             const int pos = bj ? (w & 63) : (w >> 6);
; #pragma unroll
;                             for (int n = 0; n < 2; ++n) {
;                                 const f32x4 cs = *(const f32x4*)(tcos + pos * 16 + 8 * (fq & 1) + 4 * n);
;                                 const f32x4 sn = *(const f32x4*)(tsin + pos * 16 + 8 * (fq & 1) + 4 * n);
;                                 f32x4 p; p[0] = __shfl_xor(x[bj][n][0], 32); p[1] = __shfl_xor(x[bj][n][1], 32); p[2] = __shfl_xor(x[bj][n][2], 32); p[3] = __shfl_xor(x[bj][n][3], 32);
;                                 const f32x4 sgn = (fq < 2) ? -sn : sn;
;                                 x[bj][n] = x[bj][n] * cs + p * sgn;
;                             }
;                         }
;                     }
	v_add_f32_e32 v0, v82, v249
	v_fmamk_f32 v0, v0, 0x3c800000, v216
	v_mul_f32_e32 v71, 0x4f800000, v0
	v_cmp_gt_f32_e32 vcc, s69, v0
	v_cvt_pk_bf16_f32 v70, v86, v87
	s_nop 1
	v_cndmask_b32_e32 v0, v0, v71, vcc
	v_sqrt_f32_e32 v78, v0
	v_cvt_pk_bf16_f32 v71, v74, v75
	v_cvt_pk_bf16_f32 v72, v88, v89
	v_cvt_pk_bf16_f32 v73, v76, v77
	flat_store_dwordx4 v[90:91], v[70:73] offset:64
	v_add_u32_e32 v74, -1, v78
	v_fma_f32 v75, -v74, v78, v0
	v_cmp_ge_f32_e64 s[0:1], 0, v75
	v_add_u32_e32 v75, 1, v78
	v_fma_f32 v76, -v75, v78, v0
	v_cndmask_b32_e64 v74, v78, v74, s[0:1]
	v_cmp_lt_f32_e64 s[0:1], 0, v76
	v_add_u32_e32 v77, 0xffffdf80, v173
	s_nop 0
	v_cndmask_b32_e64 v74, v74, v75, s[0:1]
	v_mul_f32_e32 v75, 0x37800000, v74
	v_cndmask_b32_e32 v74, v74, v75, vcc
	v_cmp_class_f32_e32 vcc, v0, v217
	s_nop 1
	v_cndmask_b32_e32 v0, v74, v0, vcc
	v_div_scale_f32 v75, s[0:1], v0, v0, 1.0
	v_rcp_f32_e32 v76, v75
	s_movk_i32 s0, 0x207f
	v_add_u32_e32 v74, 0x80, v173
	v_fma_f32 v70, -v75, v76, 1.0
	v_fmac_f32_e32 v76, v70, v76
	v_div_scale_f32 v70, vcc, 1.0, v0, 1.0
	v_mul_f32_e32 v71, v70, v76
	v_fma_f32 v72, -v75, v71, v70
	v_fmac_f32_e32 v71, v72, v76
	v_fma_f32 v70, -v75, v71, v70
	v_div_fmas_f32 v70, v70, v76, v71
	v_div_fixup_f32 v0, v70, v0, 1.0
	v_pk_mul_f32 v[70:71], v[66:67], v[0:1] op_sel_hi:[1,0]
	v_pk_mul_f32 v[66:67], v[68:69], v[0:1] op_sel_hi:[1,0]
	v_pk_mul_f32 v[68:69], v[164:165], v[70:71]
	v_pk_mul_f32 v[70:71], v[62:63], v[0:1] op_sel_hi:[1,0]
	v_cmp_lt_i32_e32 vcc, s0, v173
	v_pk_mul_f32 v[62:63], v[64:65], v[0:1] op_sel_hi:[1,0]
	v_pk_mul_f32 v[64:65], v[160:161], v[70:71]
	v_pk_mul_f32 v[70:71], v[58:59], v[0:1] op_sel_hi:[1,0]
	v_pk_mul_f32 v[58:59], v[60:61], v[0:1] op_sel_hi:[1,0]
	v_pk_mul_f32 v[54:55], v[54:55], v[0:1] op_sel_hi:[1,0]
	v_pk_mul_f32 v[56:57], v[56:57], v[0:1] op_sel_hi:[1,0]
	v_cndmask_b32_e32 v0, v74, v77, vcc
	v_pk_mul_f32 v[66:67], v[162:163], v[66:67]
	v_pk_mul_f32 v[62:63], v[158:159], v[62:63]
	v_pk_mul_f32 v[58:59], v[138:139], v[58:59]
	v_pk_mul_f32 v[60:61], v[140:141], v[70:71]
	v_pk_mul_f32 v[70:71], v[134:135], v[56:57]
	v_pk_mul_f32 v[72:73], v[136:137], v[54:55]
	v_cmp_gt_i32_e32 vcc, s66, v0
	s_and_saveexec_b64 s[0:1], vcc
	s_cbranch_execz .LBB0_268
	v_ashrrev_i32_e32 v54, 2, v0
	v_and_b32_e32 v54, -16, v54
	v_ashrrev_i32_e32 v55, 31, v54
	v_lshlrev_b64 v[54:55], 2, v[54:55]
	v_lshl_add_u64 v[80:81], v[150:151], 0, v[54:55]
	v_lshl_add_u64 v[82:83], v[152:153], 0, v[54:55]
	flat_load_dwordx4 v[54:57], v[80:81]
	flat_load_dwordx4 v[76:79], v[82:83]
	flat_load_dwordx4 v[240:243], v[80:81] offset:16
	flat_load_dwordx4 v[244:247], v[82:83] offset:16
	ds_bpermute_b32 v84, v174, v68
	ds_bpermute_b32 v85, v174, v69
	ds_bpermute_b32 v86, v174, v66
	ds_bpermute_b32 v87, v174, v67
	v_lshlrev_b32_e32 v0, 6, v0
	v_and_b32_e32 v0, 0x3c0, v0
	s_waitcnt vmcnt(0) lgkmcnt(0)
	v_xor_b32_e32 v75, 0x80000000, v76
	v_xor_b32_e32 v88, 0x80000000, v77
	v_xor_b32_e32 v89, 0x80000000, v78
	v_xor_b32_e32 v90, 0x80000000, v79
	v_cndmask_b32_e64 v79, v79, v90, s[4:5]
	v_cndmask_b32_e64 v78, v78, v89, s[4:5]
	v_cndmask_b32_e64 v77, v77, v88, s[4:5]
	v_cndmask_b32_e64 v76, v76, v75, s[4:5]
	v_pk_mul_f32 v[76:77], v[76:77], v[84:85]
	v_pk_mul_f32 v[78:79], v[78:79], v[86:87]
	v_pk_fma_f32 v[68:69], v[68:69], v[54:55], v[76:77]
	v_pk_fma_f32 v[66:67], v[66:67], v[56:57], v[78:79]
	ds_bpermute_b32 v80, v174, v64
	ds_bpermute_b32 v81, v174, v65
	ds_bpermute_b32 v82, v174, v62
	ds_bpermute_b32 v83, v174, v63
	ds_bpermute_b32 v87, v174, v59
	s_waitcnt vmcnt(0) lgkmcnt(0)
	v_xor_b32_e32 v75, 0x80000000, v244
	v_xor_b32_e32 v84, 0x80000000, v245
	v_xor_b32_e32 v85, 0x80000000, v246
	v_xor_b32_e32 v86, 0x80000000, v247
	v_cndmask_b32_e64 v247, v247, v86, s[4:5]
	v_cndmask_b32_e64 v246, v246, v85, s[4:5]
	v_cndmask_b32_e64 v245, v245, v84, s[4:5]
	v_cndmask_b32_e64 v244, v244, v75, s[4:5]
	v_pk_mul_f32 v[244:245], v[244:245], v[80:81]
	v_pk_mul_f32 v[246:247], v[246:247], v[82:83]
	v_lshl_add_u64 v[80:81], v[150:151], 0, v[0:1]
	v_pk_fma_f32 v[62:63], v[62:63], v[242:243], v[246:247]
	v_pk_fma_f32 v[64:65], v[64:65], v[240:241], v[244:245]
	v_lshl_add_u64 v[82:83], v[152:153], 0, v[0:1]
	flat_load_dwordx4 v[54:57], v[80:81]
	flat_load_dwordx4 v[76:79], v[82:83]
	flat_load_dwordx4 v[240:243], v[80:81] offset:16
	flat_load_dwordx4 v[244:247], v[82:83] offset:16
	ds_bpermute_b32 v84, v174, v60
	ds_bpermute_b32 v85, v174, v61
	ds_bpermute_b32 v86, v174, v58
	s_waitcnt vmcnt(0) lgkmcnt(0)
	v_xor_b32_e32 v0, 0x80000000, v76
	v_xor_b32_e32 v75, 0x80000000, v77
	v_xor_b32_e32 v88, 0x80000000, v78
	v_xor_b32_e32 v89, 0x80000000, v79
	v_cndmask_b32_e64 v79, v79, v89, s[4:5]
	v_cndmask_b32_e64 v78, v78, v88, s[4:5]
	v_cndmask_b32_e64 v77, v77, v75, s[4:5]
	v_cndmask_b32_e64 v76, v76, v0, s[4:5]
	v_pk_mul_f32 v[76:77], v[76:77], v[84:85]
	v_pk_mul_f32 v[78:79], v[78:79], v[86:87]
	v_pk_fma_f32 v[60:61], v[60:61], v[54:55], v[76:77]
	v_pk_fma_f32 v[58:59], v[58:59], v[56:57], v[78:79]
	ds_bpermute_b32 v80, v174, v72
	ds_bpermute_b32 v81, v174, v73
	ds_bpermute_b32 v82, v174, v70
	ds_bpermute_b32 v83, v174, v71
	s_waitcnt vmcnt(0) lgkmcnt(0)
	v_xor_b32_e32 v0, 0x80000000, v244
	v_xor_b32_e32 v75, 0x80000000, v245
	v_xor_b32_e32 v84, 0x80000000, v246
	v_xor_b32_e32 v85, 0x80000000, v247
	v_cndmask_b32_e64 v247, v247, v85, s[4:5]
	v_cndmask_b32_e64 v246, v246, v84, s[4:5]
	v_cndmask_b32_e64 v245, v245, v75, s[4:5]
	v_cndmask_b32_e64 v244, v244, v0, s[4:5]
	v_pk_mul_f32 v[244:245], v[244:245], v[80:81]
	v_pk_mul_f32 v[246:247], v[246:247], v[82:83]
	v_pk_fma_f32 v[72:73], v[72:73], v[240:241], v[244:245]
	v_pk_fma_f32 v[70:71], v[70:71], v[242:243], v[246:247]
; __device__ __forceinline__ unsigned cvt_pk_bf16(float lo, float hi) { unsigned r; asm volatile("v_cvt_pk_bf16_f32 %0, %1, %2" : "=v"(r) : "v"(lo), "v"(hi)); return r; }
;     __device__ __forceinline__ void operator()(const f32x4 (&acc)[2][2][4][2], const Unit& u, int wr, int wc, int fr, int fq) const {
;     ...
;                     f32x4 x[2][2]; float ss = 0.f;
; #pragma unroll
;                     for (int bj = 0; bj < 2; ++bj)
; #pragma unroll
;                         for (int n = 0; n < 2; ++n) { x[bj][n] = acc[ai][bj][m][n]; const f32x4 q = x[bj][n] * x[bj][n]; ss += (q[0] + q[1]) + (q[2] + q[3]); }
;                     ss += __shfl_xor(ss, 16); ss += __shfl_xor(ss, 32);
;                     const float rinv = 1.0f / sqrtf(ss * (1.0f / 64.0f) + LN_EPS);
; #pragma unroll
;                     for (int bj = 0; bj < 2; ++bj)
; #pragma unroll
;                         for (int n = 0; n < 2; ++n) x[bj][n] = x[bj][n] * rinv * gv[bj][n];
;                     if (w < SEQ) {
; #pragma unroll
;                         for (int bj = 0; bj < 2; ++bj) {
;                             const int pos = bj ? (w & 63) : (w >> 6);
; #pragma unroll
;                             for (int n = 0; n < 2; ++n) {
;                                 const f32x4 cs = *(const f32x4*)(tcos + pos * 16 + 8 * (fq & 1) + 4 * n);
;                                 const f32x4 sn = *(const f32x4*)(tsin + pos * 16 + 8 * (fq & 1) + 4 * n);
;                                 f32x4 p; p[0] = __shfl_xor(x[bj][n][0], 32); p[1] = __shfl_xor(x[bj][n][1], 32); p[2] = __shfl_xor(x[bj][n][2], 32); p[3] = __shfl_xor(x[bj][n][3], 32);
;                                 const f32x4 sgn = (fq < 2) ? -sn : sn;
;                                 x[bj][n] = x[bj][n] * cs + p * sgn;
;                             }
;                         }
;                     }
;                     bf16_t* rowp = O + (size_t)row * DIN + ocol;
; #pragma unroll
;                     for (int bj = 0; bj < 2; ++bj) { u32x4 wv; wv.x = cvt_pk_bf16(x[bj][0][0], x[bj][0][1]); wv.y = cvt_pk_bf16(x[bj][0][2], x[bj][0][3]); wv.z = cvt_pk_bf16(x[bj][1][0], x[bj][1][1]); wv.w = cvt_pk_bf16(x[bj][1][2], x[bj][1][3]);
;                         *(u32x4*)(rowp + 32 * bj) = wv; }
.LBB0_268:
	s_or_b64 exec, exec, s[0:1]
	v_mov_b64_e32 v[54:55], s[12:13]
	v_mad_i64_i32 v[54:55], s[0:1], v74, s80, v[54:55]
	v_lshl_add_u64 v[74:75], v[118:119], 1, v[54:55]
	v_cvt_pk_bf16_f32 v54, v68, v69
	v_cvt_pk_bf16_f32 v55, v66, v67
	v_cvt_pk_bf16_f32 v56, v64, v65
	v_cvt_pk_bf16_f32 v57, v62, v63
	flat_store_dwordx4 v[74:75], v[54:57]
	v_pk_mul_f32 v[64:65], v[40:41], v[40:41]
	v_pk_mul_f32 v[66:67], v[38:39], v[38:39]
	v_cvt_pk_bf16_f32 v54, v60, v61
	v_cvt_pk_bf16_f32 v55, v58, v59
	v_cvt_pk_bf16_f32 v56, v72, v73
	v_cvt_pk_bf16_f32 v57, v70, v71
	flat_store_dwordx4 v[74:75], v[54:57] offset:64
	s_movk_i32 s0, 0x206f
	v_add_u32_e32 v58, 0x90, v173
	v_pk_mul_f32 v[54:55], v[52:53], v[52:53]
	v_pk_mul_f32 v[56:57], v[50:51], v[50:51]
	v_add_u32_e32 v59, 0xffffdf90, v173
	v_pk_mov_b32 v[60:61], v[56:57], v[54:55] op_sel:[1,0]
	v_mov_b32_e32 v57, v55
	v_pk_add_f32 v[54:55], v[60:61], v[56:57]
	v_pk_mul_f32 v[56:57], v[48:49], v[48:49]
	v_pk_mul_f32 v[60:61], v[46:47], v[46:47]
	v_pk_add_f32 v[54:55], v[54:55], v[54:55] op_sel_hi:[0,1]
	v_pk_mov_b32 v[62:63], v[60:61], v[56:57] op_sel:[1,0]
	v_mov_b32_e32 v61, v57
	v_pk_add_f32 v[56:57], v[62:63], v[60:61]
	v_pk_mul_f32 v[60:61], v[44:45], v[44:45]
	v_pk_add_f32 v[56:57], v[56:57], v[56:57] op_sel_hi:[0,1]
	v_pk_mul_f32 v[62:63], v[42:43], v[42:43]
	v_add_f32_e32 v61, v60, v61
	v_add_f32_e32 v63, v62, v63
	v_mov_b32_e32 v62, v66
	v_mov_b32_e32 v60, v67
	v_mov_b32_e32 v56, v64
	v_mov_b32_e32 v54, v65
	v_pk_add_f32 v[60:61], v[62:63], v[60:61]
	v_pk_add_f32 v[54:55], v[56:57], v[54:55]
	v_cmp_lt_i32_e64 s[0:1], s0, v173
	v_pk_add_f32 v[54:55], v[60:61], v[54:55]
	s_nop 0
	v_add_f32_e32 v0, v54, v55
	v_mov_b32_e32 v54, v0
	v_mov_b32_e32 v248, v0
	s_nop 1
	v_permlane16_swap_b32_e32 v54, v248
	s_waitcnt lgkmcnt(0)
	v_add_f32_e32 v0, v54, v248
	v_mov_b32_e32 v54, v0
	v_mov_b32_e32 v249, v0
	s_nop 1
	v_permlane32_swap_b32_e32 v54, v249
	s_waitcnt lgkmcnt(0)
	v_add_f32_e32 v0, v54, v249
	v_fmamk_f32 v0, v0, 0x3c800000, v216
	v_cmp_gt_f32_e32 vcc, s69, v0
	v_mul_f32_e32 v54, 0x4f800000, v0
	s_nop 0
	v_cndmask_b32_e32 v0, v0, v54, vcc
	v_sqrt_f32_e32 v54, v0
	s_nop 0
	v_add_u32_e32 v55, -1, v54
	v_fma_f32 v56, -v55, v54, v0
	v_cmp_ge_f32_e64 s[8:9], 0, v56
	v_add_u32_e32 v56, 1, v54
	s_nop 0
	v_cndmask_b32_e64 v55, v54, v55, s[8:9]
	v_fma_f32 v54, -v56, v54, v0
	v_cmp_lt_f32_e64 s[8:9], 0, v54
	s_nop 1
	v_cndmask_b32_e64 v54, v55, v56, s[8:9]
	v_mul_f32_e32 v55, 0x37800000, v54
	v_cndmask_b32_e32 v54, v54, v55, vcc
	v_cmp_class_f32_e32 vcc, v0, v217
	s_nop 1
	v_cndmask_b32_e32 v0, v54, v0, vcc
	v_div_scale_f32 v54, s[2:3], v0, v0, 1.0
	v_rcp_f32_e32 v55, v54
	s_nop 0
	v_fma_f32 v56, -v54, v55, 1.0
	v_fmac_f32_e32 v55, v56, v55
	v_div_scale_f32 v56, vcc, 1.0, v0, 1.0
	v_mul_f32_e32 v57, v56, v55
	v_fma_f32 v60, -v54, v57, v56
	v_fmac_f32_e32 v57, v60, v55
	v_fma_f32 v54, -v54, v57, v56
	v_div_fmas_f32 v54, v54, v55, v57
	v_div_fixup_f32 v0, v54, v0, 1.0
	v_pk_mul_f32 v[54:55], v[50:51], v[0:1] op_sel_hi:[1,0]
	v_pk_mul_f32 v[50:51], v[52:53], v[0:1] op_sel_hi:[1,0]
	v_pk_mul_f32 v[52:53], v[164:165], v[54:55]
	v_pk_mul_f32 v[54:55], v[46:47], v[0:1] op_sel_hi:[1,0]
	v_pk_mul_f32 v[46:47], v[48:49], v[0:1] op_sel_hi:[1,0]
	v_pk_mul_f32 v[48:49], v[160:161], v[54:55]
	v_pk_mul_f32 v[54:55], v[42:43], v[0:1] op_sel_hi:[1,0]
	v_pk_mul_f32 v[42:43], v[44:45], v[0:1] op_sel_hi:[1,0]
	v_pk_mul_f32 v[38:39], v[38:39], v[0:1] op_sel_hi:[1,0]
	v_pk_mul_f32 v[40:41], v[40:41], v[0:1] op_sel_hi:[1,0]
	v_cndmask_b32_e64 v0, v58, v59, s[0:1]
	v_pk_mul_f32 v[50:51], v[162:163], v[50:51]
	v_pk_mul_f32 v[46:47], v[158:159], v[46:47]
	v_pk_mul_f32 v[42:43], v[138:139], v[42:43]
	v_pk_mul_f32 v[54:55], v[140:141], v[54:55]
	v_pk_mul_f32 v[44:45], v[134:135], v[40:41]
	v_pk_mul_f32 v[56:57], v[136:137], v[38:39]
	v_cmp_gt_i32_e32 vcc, s66, v0
	s_and_saveexec_b64 s[0:1], vcc
	s_cbranch_execz .LBB0_270
	v_ashrrev_i32_e32 v38, 2, v0
	v_and_b32_e32 v38, -16, v38
	v_ashrrev_i32_e32 v39, 31, v38
	v_lshlrev_b64 v[38:39], 2, v[38:39]
	v_lshl_add_u64 v[64:65], v[150:151], 0, v[38:39]
	v_lshl_add_u64 v[66:67], v[152:153], 0, v[38:39]
	flat_load_dwordx4 v[38:41], v[64:65]
	flat_load_dwordx4 v[60:63], v[66:67]
	flat_load_dwordx4 v[240:243], v[64:65] offset:16
	flat_load_dwordx4 v[244:247], v[66:67] offset:16
	ds_bpermute_b32 v68, v174, v52
	ds_bpermute_b32 v69, v174, v53
	ds_bpermute_b32 v70, v174, v50
	ds_bpermute_b32 v71, v174, v51
	v_lshlrev_b32_e32 v0, 6, v0
	v_and_b32_e32 v0, 0x7c0, v0
	s_waitcnt vmcnt(0) lgkmcnt(0)
	v_xor_b32_e32 v59, 0x80000000, v60
	v_xor_b32_e32 v72, 0x80000000, v61
	v_xor_b32_e32 v73, 0x80000000, v62
	v_xor_b32_e32 v74, 0x80000000, v63
	v_cndmask_b32_e64 v63, v63, v74, s[4:5]
	v_cndmask_b32_e64 v62, v62, v73, s[4:5]
	v_cndmask_b32_e64 v61, v61, v72, s[4:5]
	v_cndmask_b32_e64 v60, v60, v59, s[4:5]
	v_pk_mul_f32 v[60:61], v[60:61], v[68:69]
	v_pk_mul_f32 v[62:63], v[62:63], v[70:71]
	v_pk_fma_f32 v[52:53], v[52:53], v[38:39], v[60:61]
	v_pk_fma_f32 v[50:51], v[50:51], v[40:41], v[62:63]
	ds_bpermute_b32 v64, v174, v48
	ds_bpermute_b32 v65, v174, v49
	ds_bpermute_b32 v66, v174, v46
	ds_bpermute_b32 v67, v174, v47
	ds_bpermute_b32 v71, v174, v43
	s_waitcnt vmcnt(0) lgkmcnt(0)
; __device__ __forceinline__ unsigned cvt_pk_bf16(float lo, float hi) { unsigned r; asm volatile("v_cvt_pk_bf16_f32 %0, %1, %2" : "=v"(r) : "v"(lo), "v"(hi)); return r; }
;     __device__ __forceinline__ void operator()(const f32x4 (&acc)[2][2][4][2], const Unit& u, int wr, int wc, int fr, int fq) const {
;     ...
;                     f32x4 x[2][2]; float ss = 0.f;
; #pragma unroll
;                     for (int bj = 0; bj < 2; ++bj)
; #pragma unroll
;                         for (int n = 0; n < 2; ++n) { x[bj][n] = acc[ai][bj][m][n]; const f32x4 q = x[bj][n] * x[bj][n]; ss += (q[0] + q[1]) + (q[2] + q[3]); }
;                     ss += __shfl_xor(ss, 16); ss += __shfl_xor(ss, 32);
;                     const float rinv = 1.0f / sqrtf(ss * (1.0f / 64.0f) + LN_EPS);
; #pragma unroll
;                     for (int bj = 0; bj < 2; ++bj)
; #pragma unroll
;                         for (int n = 0; n < 2; ++n) x[bj][n] = x[bj][n] * rinv * gv[bj][n];
;                     if (w < SEQ) {
; #pragma unroll
;                         for (int bj = 0; bj < 2; ++bj) {
;                             const int pos = bj ? (w & 63) : (w >> 6);
; #pragma unroll
;                             for (int n = 0; n < 2; ++n) {
;                                 const f32x4 cs = *(const f32x4*)(tcos + pos * 16 + 8 * (fq & 1) + 4 * n);
;                                 const f32x4 sn = *(const f32x4*)(tsin + pos * 16 + 8 * (fq & 1) + 4 * n);
;                                 f32x4 p; p[0] = __shfl_xor(x[bj][n][0], 32); p[1] = __shfl_xor(x[bj][n][1], 32); p[2] = __shfl_xor(x[bj][n][2], 32); p[3] = __shfl_xor(x[bj][n][3], 32);
;                                 const f32x4 sgn = (fq < 2) ? -sn : sn;
;                                 x[bj][n] = x[bj][n] * cs + p * sgn;
;                             }
;                         }
;                     }
;                     bf16_t* rowp = O + (size_t)row * DIN + ocol;
; #pragma unroll
;                     for (int bj = 0; bj < 2; ++bj) { u32x4 wv; wv.x = cvt_pk_bf16(x[bj][0][0], x[bj][0][1]); wv.y = cvt_pk_bf16(x[bj][0][2], x[bj][0][3]); wv.z = cvt_pk_bf16(x[bj][1][0], x[bj][1][1]); wv.w = cvt_pk_bf16(x[bj][1][2], x[bj][1][3]);
;                         *(u32x4*)(rowp + 32 * bj) = wv; }
	v_xor_b32_e32 v59, 0x80000000, v244
	v_xor_b32_e32 v68, 0x80000000, v245
	v_xor_b32_e32 v69, 0x80000000, v246
	v_xor_b32_e32 v70, 0x80000000, v247
	v_cndmask_b32_e64 v247, v247, v70, s[4:5]
	v_cndmask_b32_e64 v246, v246, v69, s[4:5]
	v_cndmask_b32_e64 v245, v245, v68, s[4:5]
	v_cndmask_b32_e64 v244, v244, v59, s[4:5]
	v_pk_mul_f32 v[244:245], v[244:245], v[64:65]
	v_pk_mul_f32 v[246:247], v[246:247], v[66:67]
	v_lshl_add_u64 v[64:65], v[150:151], 0, v[0:1]
	v_pk_fma_f32 v[46:47], v[46:47], v[242:243], v[246:247]
	v_pk_fma_f32 v[48:49], v[48:49], v[240:241], v[244:245]
	v_lshl_add_u64 v[66:67], v[152:153], 0, v[0:1]
	flat_load_dwordx4 v[38:41], v[64:65]
	flat_load_dwordx4 v[60:63], v[66:67]
	flat_load_dwordx4 v[240:243], v[64:65] offset:16
	flat_load_dwordx4 v[244:247], v[66:67] offset:16
	ds_bpermute_b32 v68, v174, v54
	ds_bpermute_b32 v69, v174, v55
	ds_bpermute_b32 v70, v174, v42
	s_waitcnt vmcnt(0) lgkmcnt(0)
	v_xor_b32_e32 v0, 0x80000000, v60
	v_xor_b32_e32 v59, 0x80000000, v61
	v_xor_b32_e32 v72, 0x80000000, v62
	v_xor_b32_e32 v73, 0x80000000, v63
	v_cndmask_b32_e64 v63, v63, v73, s[4:5]
	v_cndmask_b32_e64 v62, v62, v72, s[4:5]
	v_cndmask_b32_e64 v61, v61, v59, s[4:5]
	v_cndmask_b32_e64 v60, v60, v0, s[4:5]
	v_pk_mul_f32 v[60:61], v[60:61], v[68:69]
	v_pk_mul_f32 v[62:63], v[62:63], v[70:71]
	v_pk_fma_f32 v[54:55], v[54:55], v[38:39], v[60:61]
	v_pk_fma_f32 v[42:43], v[42:43], v[40:41], v[62:63]
	ds_bpermute_b32 v64, v174, v56
	ds_bpermute_b32 v65, v174, v57
	ds_bpermute_b32 v66, v174, v44
	ds_bpermute_b32 v67, v174, v45
	s_waitcnt vmcnt(0) lgkmcnt(0)
	v_xor_b32_e32 v0, 0x80000000, v244
	v_xor_b32_e32 v59, 0x80000000, v245
	v_xor_b32_e32 v68, 0x80000000, v246
	v_xor_b32_e32 v69, 0x80000000, v247
	v_cndmask_b32_e64 v247, v247, v69, s[4:5]
	v_cndmask_b32_e64 v246, v246, v68, s[4:5]
	v_cndmask_b32_e64 v245, v245, v59, s[4:5]
	v_cndmask_b32_e64 v244, v244, v0, s[4:5]
	v_pk_mul_f32 v[244:245], v[244:245], v[64:65]
	v_pk_mul_f32 v[246:247], v[246:247], v[66:67]
	v_pk_fma_f32 v[56:57], v[56:57], v[240:241], v[244:245]
	v_pk_fma_f32 v[44:45], v[44:45], v[242:243], v[246:247]
.LBB0_270:
	s_or_b64 exec, exec, s[0:1]
	v_pk_mul_f32 v[40:41], v[36:37], v[36:37]
	v_pk_mul_f32 v[60:61], v[34:35], v[34:35]
	v_pk_mul_f32 v[66:67], v[24:25], v[24:25]
	v_pk_mov_b32 v[62:63], v[60:61], v[40:41] op_sel:[1,0]
	v_mov_b32_e32 v61, v41
	v_pk_add_f32 v[40:41], v[62:63], v[60:61]
	v_pk_mul_f32 v[60:61], v[32:33], v[32:33]
	v_pk_mul_f32 v[62:63], v[30:31], v[30:31]
	v_pk_add_f32 v[40:41], v[40:41], v[40:41] op_sel_hi:[0,1]
	v_pk_mov_b32 v[64:65], v[62:63], v[60:61] op_sel:[1,0]
	v_mov_b32_e32 v63, v61
	v_pk_add_f32 v[60:61], v[64:65], v[62:63]
	v_pk_mul_f32 v[62:63], v[28:29], v[28:29]
	v_pk_add_f32 v[60:61], v[60:61], v[60:61] op_sel_hi:[0,1]
	v_pk_mul_f32 v[64:65], v[26:27], v[26:27]
	v_pk_mul_f32 v[68:69], v[22:23], v[22:23]
	v_add_f32_e32 v65, v64, v65
	v_add_f32_e32 v63, v62, v63
	v_mov_b32_e32 v64, v68
	v_mov_b32_e32 v62, v69
	v_mov_b32_e32 v60, v66
	v_mov_b32_e32 v40, v67
	v_pk_add_f32 v[62:63], v[64:65], v[62:63]
	v_pk_add_f32 v[40:41], v[60:61], v[40:41]
	v_mov_b64_e32 v[38:39], s[12:13]
	v_pk_add_f32 v[40:41], v[62:63], v[40:41]
	v_mad_i64_i32 v[38:39], s[0:1], v58, s80, v[38:39]
	v_add_f32_e32 v0, v40, v41
	v_mov_b32_e32 v40, v0
	v_mov_b32_e32 v248, v0
	s_nop 1
	v_permlane16_swap_b32_e32 v40, v248
	v_lshl_add_u64 v[58:59], v[118:119], 1, v[38:39]
	v_cvt_pk_bf16_f32 v38, v52, v53
	v_cvt_pk_bf16_f32 v39, v50, v51
	s_waitcnt lgkmcnt(0)
	v_add_f32_e32 v0, v40, v248
	v_mov_b32_e32 v50, v0
	v_mov_b32_e32 v249, v0
	s_nop 1
	v_permlane32_swap_b32_e32 v50, v249
	v_cvt_pk_bf16_f32 v40, v48, v49
	v_cvt_pk_bf16_f32 v41, v46, v47
	flat_store_dwordx4 v[58:59], v[38:41]
	s_waitcnt lgkmcnt(0)
	v_add_f32_e32 v0, v50, v249
	v_fmamk_f32 v0, v0, 0x3c800000, v216
	v_mul_f32_e32 v39, 0x4f800000, v0
	v_cmp_gt_f32_e32 vcc, s69, v0
	v_cvt_pk_bf16_f32 v38, v54, v55
	s_nop 1
	v_cndmask_b32_e32 v0, v0, v39, vcc
	v_sqrt_f32_e32 v46, v0
	v_cvt_pk_bf16_f32 v39, v42, v43
	v_cvt_pk_bf16_f32 v40, v56, v57
	v_cvt_pk_bf16_f32 v41, v44, v45
	flat_store_dwordx4 v[58:59], v[38:41] offset:64
	v_add_u32_e32 v42, -1, v46
	v_fma_f32 v43, -v42, v46, v0
	v_cmp_ge_f32_e64 s[0:1], 0, v43
	v_add_u32_e32 v43, 1, v46
	v_fma_f32 v44, -v43, v46, v0
	v_cndmask_b32_e64 v42, v46, v42, s[0:1]
	v_cmp_lt_f32_e64 s[0:1], 0, v44
	v_add_u32_e32 v45, 0xffffdfa0, v173
	s_nop 0
	v_cndmask_b32_e64 v42, v42, v43, s[0:1]
	v_mul_f32_e32 v43, 0x37800000, v42
	v_cndmask_b32_e32 v42, v42, v43, vcc
	v_cmp_class_f32_e32 vcc, v0, v217
	s_nop 1
	v_cndmask_b32_e32 v0, v42, v0, vcc
	v_div_scale_f32 v43, s[0:1], v0, v0, 1.0
	v_rcp_f32_e32 v44, v43
	s_movk_i32 s0, 0x205f
	v_add_u32_e32 v42, 0xa0, v173
	v_fma_f32 v38, -v43, v44, 1.0
	v_fmac_f32_e32 v44, v38, v44
	v_div_scale_f32 v38, vcc, 1.0, v0, 1.0
	v_mul_f32_e32 v39, v38, v44
	v_fma_f32 v40, -v43, v39, v38
	v_fmac_f32_e32 v39, v40, v44
	v_fma_f32 v38, -v43, v39, v38
	v_div_fmas_f32 v38, v38, v44, v39
	v_div_fixup_f32 v0, v38, v0, 1.0
	v_pk_mul_f32 v[38:39], v[34:35], v[0:1] op_sel_hi:[1,0]
	v_pk_mul_f32 v[34:35], v[36:37], v[0:1] op_sel_hi:[1,0]
	v_pk_mul_f32 v[36:37], v[164:165], v[38:39]
	v_pk_mul_f32 v[38:39], v[30:31], v[0:1] op_sel_hi:[1,0]
	v_cmp_lt_i32_e32 vcc, s0, v173
	v_pk_mul_f32 v[30:31], v[32:33], v[0:1] op_sel_hi:[1,0]
	v_pk_mul_f32 v[32:33], v[160:161], v[38:39]
	v_pk_mul_f32 v[38:39], v[26:27], v[0:1] op_sel_hi:[1,0]
	v_pk_mul_f32 v[26:27], v[28:29], v[0:1] op_sel_hi:[1,0]
	v_pk_mul_f32 v[22:23], v[22:23], v[0:1] op_sel_hi:[1,0]
	v_pk_mul_f32 v[24:25], v[24:25], v[0:1] op_sel_hi:[1,0]
	v_cndmask_b32_e32 v0, v42, v45, vcc
	v_pk_mul_f32 v[34:35], v[162:163], v[34:35]
	v_pk_mul_f32 v[30:31], v[158:159], v[30:31]
	v_pk_mul_f32 v[26:27], v[138:139], v[26:27]
	v_pk_mul_f32 v[28:29], v[140:141], v[38:39]
	v_pk_mul_f32 v[38:39], v[134:135], v[24:25]
	v_pk_mul_f32 v[40:41], v[136:137], v[22:23]
	v_cmp_gt_i32_e32 vcc, s66, v0
	s_and_saveexec_b64 s[0:1], vcc
	s_cbranch_execz .LBB0_272
; __device__ __forceinline__ unsigned cvt_pk_bf16(float lo, float hi) { unsigned r; asm volatile("v_cvt_pk_bf16_f32 %0, %1, %2" : "=v"(r) : "v"(lo), "v"(hi)); return r; }
;     __device__ __forceinline__ void operator()(const f32x4 (&acc)[2][2][4][2], const Unit& u, int wr, int wc, int fr, int fq) const {
;     ...
;                     f32x4 x[2][2]; float ss = 0.f;
; #pragma unroll
;                     for (int bj = 0; bj < 2; ++bj)
; #pragma unroll
;                         for (int n = 0; n < 2; ++n) { x[bj][n] = acc[ai][bj][m][n]; const f32x4 q = x[bj][n] * x[bj][n]; ss += (q[0] + q[1]) + (q[2] + q[3]); }
;                     ss += __shfl_xor(ss, 16); ss += __shfl_xor(ss, 32);
;                     const float rinv = 1.0f / sqrtf(ss * (1.0f / 64.0f) + LN_EPS);
; #pragma unroll
;                     for (int bj = 0; bj < 2; ++bj)
; #pragma unroll
;                         for (int n = 0; n < 2; ++n) x[bj][n] = x[bj][n] * rinv * gv[bj][n];
;                     if (w < SEQ) {
; #pragma unroll
;                         for (int bj = 0; bj < 2; ++bj) {
;                             const int pos = bj ? (w & 63) : (w >> 6);
; #pragma unroll
;                             for (int n = 0; n < 2; ++n) {
;                                 const f32x4 cs = *(const f32x4*)(tcos + pos * 16 + 8 * (fq & 1) + 4 * n);
;                                 const f32x4 sn = *(const f32x4*)(tsin + pos * 16 + 8 * (fq & 1) + 4 * n);
;                                 f32x4 p; p[0] = __shfl_xor(x[bj][n][0], 32); p[1] = __shfl_xor(x[bj][n][1], 32); p[2] = __shfl_xor(x[bj][n][2], 32); p[3] = __shfl_xor(x[bj][n][3], 32);
;                                 const f32x4 sgn = (fq < 2) ? -sn : sn;
;                                 x[bj][n] = x[bj][n] * cs + p * sgn;
;                             }
;                         }
;                     }
;                     bf16_t* rowp = O + (size_t)row * DIN + ocol;
; #pragma unroll
;                     for (int bj = 0; bj < 2; ++bj) { u32x4 wv; wv.x = cvt_pk_bf16(x[bj][0][0], x[bj][0][1]); wv.y = cvt_pk_bf16(x[bj][0][2], x[bj][0][3]); wv.z = cvt_pk_bf16(x[bj][1][0], x[bj][1][1]); wv.w = cvt_pk_bf16(x[bj][1][2], x[bj][1][3]);
;                         *(u32x4*)(rowp + 32 * bj) = wv; }
	v_ashrrev_i32_e32 v22, 2, v0
	v_and_b32_e32 v22, -16, v22
	v_ashrrev_i32_e32 v23, 31, v22
	v_lshlrev_b64 v[22:23], 2, v[22:23]
	v_lshl_add_u64 v[48:49], v[150:151], 0, v[22:23]
	v_lshl_add_u64 v[50:51], v[152:153], 0, v[22:23]
	flat_load_dwordx4 v[22:25], v[48:49]
	flat_load_dwordx4 v[44:47], v[50:51]
	flat_load_dwordx4 v[240:243], v[48:49] offset:16
	flat_load_dwordx4 v[244:247], v[50:51] offset:16
	ds_bpermute_b32 v52, v174, v36
	ds_bpermute_b32 v53, v174, v37
	ds_bpermute_b32 v54, v174, v34
	ds_bpermute_b32 v55, v174, v35
	v_lshlrev_b32_e32 v0, 6, v0
	v_and_b32_e32 v0, 0xbc0, v0
	s_waitcnt vmcnt(0) lgkmcnt(0)
	v_xor_b32_e32 v43, 0x80000000, v44
	v_xor_b32_e32 v56, 0x80000000, v45
	v_xor_b32_e32 v57, 0x80000000, v46
	v_xor_b32_e32 v58, 0x80000000, v47
	v_cndmask_b32_e64 v47, v47, v58, s[4:5]
	v_cndmask_b32_e64 v46, v46, v57, s[4:5]
	v_cndmask_b32_e64 v45, v45, v56, s[4:5]
	v_cndmask_b32_e64 v44, v44, v43, s[4:5]
	v_pk_mul_f32 v[44:45], v[44:45], v[52:53]
	v_pk_mul_f32 v[46:47], v[46:47], v[54:55]
	v_pk_fma_f32 v[36:37], v[36:37], v[22:23], v[44:45]
	v_pk_fma_f32 v[34:35], v[34:35], v[24:25], v[46:47]
	ds_bpermute_b32 v48, v174, v32
	ds_bpermute_b32 v49, v174, v33
	ds_bpermute_b32 v50, v174, v30
	ds_bpermute_b32 v51, v174, v31
	ds_bpermute_b32 v55, v174, v27
	s_waitcnt vmcnt(0) lgkmcnt(0)
	v_xor_b32_e32 v43, 0x80000000, v244
	v_xor_b32_e32 v52, 0x80000000, v245
	v_xor_b32_e32 v53, 0x80000000, v246
	v_xor_b32_e32 v54, 0x80000000, v247
	v_cndmask_b32_e64 v247, v247, v54, s[4:5]
	v_cndmask_b32_e64 v246, v246, v53, s[4:5]
	v_cndmask_b32_e64 v245, v245, v52, s[4:5]
	v_cndmask_b32_e64 v244, v244, v43, s[4:5]
	v_pk_mul_f32 v[244:245], v[244:245], v[48:49]
	v_pk_mul_f32 v[246:247], v[246:247], v[50:51]
	v_lshl_add_u64 v[48:49], v[150:151], 0, v[0:1]
	v_pk_fma_f32 v[30:31], v[30:31], v[242:243], v[246:247]
	v_pk_fma_f32 v[32:33], v[32:33], v[240:241], v[244:245]
	v_lshl_add_u64 v[50:51], v[152:153], 0, v[0:1]
	flat_load_dwordx4 v[22:25], v[48:49]
	flat_load_dwordx4 v[44:47], v[50:51]
	flat_load_dwordx4 v[240:243], v[48:49] offset:16
	flat_load_dwordx4 v[244:247], v[50:51] offset:16
	ds_bpermute_b32 v52, v174, v28
	ds_bpermute_b32 v53, v174, v29
	ds_bpermute_b32 v54, v174, v26
	s_waitcnt vmcnt(0) lgkmcnt(0)
	v_xor_b32_e32 v0, 0x80000000, v44
	v_xor_b32_e32 v43, 0x80000000, v45
	v_xor_b32_e32 v56, 0x80000000, v46
	v_xor_b32_e32 v57, 0x80000000, v47
	v_cndmask_b32_e64 v47, v47, v57, s[4:5]
	v_cndmask_b32_e64 v46, v46, v56, s[4:5]
	v_cndmask_b32_e64 v45, v45, v43, s[4:5]
	v_cndmask_b32_e64 v44, v44, v0, s[4:5]
	v_pk_mul_f32 v[44:45], v[44:45], v[52:53]
	v_pk_mul_f32 v[46:47], v[46:47], v[54:55]
	v_pk_fma_f32 v[28:29], v[28:29], v[22:23], v[44:45]
	v_pk_fma_f32 v[26:27], v[26:27], v[24:25], v[46:47]
	ds_bpermute_b32 v48, v174, v40
	ds_bpermute_b32 v49, v174, v41
	ds_bpermute_b32 v50, v174, v38
	ds_bpermute_b32 v51, v174, v39
	s_waitcnt vmcnt(0) lgkmcnt(0)
	v_xor_b32_e32 v0, 0x80000000, v244
	v_xor_b32_e32 v43, 0x80000000, v245
	v_xor_b32_e32 v52, 0x80000000, v246
	v_xor_b32_e32 v53, 0x80000000, v247
	v_cndmask_b32_e64 v247, v247, v53, s[4:5]
	v_cndmask_b32_e64 v246, v246, v52, s[4:5]
	v_cndmask_b32_e64 v245, v245, v43, s[4:5]
	v_cndmask_b32_e64 v244, v244, v0, s[4:5]
	v_pk_mul_f32 v[244:245], v[244:245], v[48:49]
	v_pk_mul_f32 v[246:247], v[246:247], v[50:51]
	v_pk_fma_f32 v[40:41], v[40:41], v[240:241], v[244:245]
	v_pk_fma_f32 v[38:39], v[38:39], v[242:243], v[246:247]
.LBB0_272:
	s_or_b64 exec, exec, s[0:1]
	v_mov_b64_e32 v[22:23], s[12:13]
	v_mad_i64_i32 v[22:23], s[0:1], v42, s80, v[22:23]
	v_lshl_add_u64 v[42:43], v[118:119], 1, v[22:23]
	v_cvt_pk_bf16_f32 v22, v36, v37
	v_cvt_pk_bf16_f32 v23, v34, v35
	v_cvt_pk_bf16_f32 v24, v32, v33
	v_cvt_pk_bf16_f32 v25, v30, v31
	flat_store_dwordx4 v[42:43], v[22:25]
	v_pk_mul_f32 v[32:33], v[4:5], v[4:5]
	v_pk_mul_f32 v[34:35], v[2:3], v[2:3]
	v_cvt_pk_bf16_f32 v22, v28, v29
	v_cvt_pk_bf16_f32 v23, v26, v27
	v_cvt_pk_bf16_f32 v24, v40, v41
	v_cvt_pk_bf16_f32 v25, v38, v39
	flat_store_dwordx4 v[42:43], v[22:25] offset:64
	s_movk_i32 s0, 0x204f
	v_add_u32_e32 v26, 0xb0, v173
	v_pk_mul_f32 v[22:23], v[20:21], v[20:21]
	v_pk_mul_f32 v[24:25], v[18:19], v[18:19]
	v_add_u32_e32 v27, 0xffffdfb0, v173
	v_pk_mov_b32 v[28:29], v[24:25], v[22:23] op_sel:[1,0]
	v_mov_b32_e32 v25, v23
	v_pk_add_f32 v[22:23], v[28:29], v[24:25]
	v_pk_mul_f32 v[24:25], v[12:13], v[12:13]
	v_pk_mul_f32 v[28:29], v[10:11], v[10:11]
	v_pk_add_f32 v[22:23], v[22:23], v[22:23] op_sel_hi:[0,1]
	v_pk_mov_b32 v[30:31], v[28:29], v[24:25] op_sel:[1,0]
	v_mov_b32_e32 v29, v25
	v_pk_add_f32 v[24:25], v[30:31], v[28:29]
	v_pk_mul_f32 v[28:29], v[8:9], v[8:9]
	v_pk_add_f32 v[24:25], v[24:25], v[24:25] op_sel_hi:[0,1]
	v_pk_mul_f32 v[30:31], v[6:7], v[6:7]
	v_add_f32_e32 v29, v28, v29
	v_add_f32_e32 v31, v30, v31
	v_mov_b32_e32 v30, v34
	v_mov_b32_e32 v28, v35
	v_mov_b32_e32 v24, v32
	v_mov_b32_e32 v22, v33
	v_pk_add_f32 v[28:29], v[30:31], v[28:29]
	v_pk_add_f32 v[22:23], v[24:25], v[22:23]
	v_cmp_lt_i32_e64 s[0:1], s0, v173
	v_pk_add_f32 v[22:23], v[28:29], v[22:23]
	s_nop 0
	v_add_f32_e32 v0, v22, v23
	v_mov_b32_e32 v22, v0
	v_mov_b32_e32 v248, v0
	s_nop 1
	v_permlane16_swap_b32_e32 v22, v248
	s_waitcnt lgkmcnt(0)
	v_add_f32_e32 v0, v22, v248
	v_mov_b32_e32 v22, v0
	v_mov_b32_e32 v249, v0
	s_nop 1
	v_permlane32_swap_b32_e32 v22, v249
	s_waitcnt lgkmcnt(0)
;     __device__ __forceinline__ void operator()(const f32x4 (&acc)[2][2][4][2], const Unit& u, int wr, int wc, int fr, int fq) const {
;     ...
;                     ss += __shfl_xor(ss, 16); ss += __shfl_xor(ss, 32);
;                     const float rinv = 1.0f / sqrtf(ss * (1.0f / 64.0f) + LN_EPS);
; #pragma unroll
;                     for (int bj = 0; bj < 2; ++bj)
; #pragma unroll
;                         for (int n = 0; n < 2; ++n) x[bj][n] = x[bj][n] * rinv * gv[bj][n];
;                     if (w < SEQ) {
; #pragma unroll
;                         for (int bj = 0; bj < 2; ++bj) {
;                             const int pos = bj ? (w & 63) : (w >> 6);
; #pragma unroll
;                             for (int n = 0; n < 2; ++n) {
;                                 const f32x4 cs = *(const f32x4*)(tcos + pos * 16 + 8 * (fq & 1) + 4 * n);
;                                 const f32x4 sn = *(const f32x4*)(tsin + pos * 16 + 8 * (fq & 1) + 4 * n);
;                                 f32x4 p; p[0] = __shfl_xor(x[bj][n][0], 32); p[1] = __shfl_xor(x[bj][n][1], 32); p[2] = __shfl_xor(x[bj][n][2], 32); p[3] = __shfl_xor(x[bj][n][3], 32);
;                                 const f32x4 sgn = (fq < 2) ? -sn : sn;
;                                 x[bj][n] = x[bj][n] * cs + p * sgn;
;                             }
;                         }
;                     }
	v_add_f32_e32 v0, v22, v249
	v_fmamk_f32 v0, v0, 0x3c800000, v216
	v_cmp_gt_f32_e32 vcc, s69, v0
	v_mul_f32_e32 v22, 0x4f800000, v0
	s_nop 0
	v_cndmask_b32_e32 v0, v0, v22, vcc
	v_sqrt_f32_e32 v22, v0
	s_nop 0
	v_add_u32_e32 v23, -1, v22
	v_fma_f32 v24, -v23, v22, v0
	v_cmp_ge_f32_e64 s[8:9], 0, v24
	v_add_u32_e32 v24, 1, v22
	s_nop 0
	v_cndmask_b32_e64 v23, v22, v23, s[8:9]
	v_fma_f32 v22, -v24, v22, v0
	v_cmp_lt_f32_e64 s[8:9], 0, v22
	s_nop 1
	v_cndmask_b32_e64 v22, v23, v24, s[8:9]
	v_mul_f32_e32 v23, 0x37800000, v22
	v_cndmask_b32_e32 v22, v22, v23, vcc
	v_cmp_class_f32_e32 vcc, v0, v217
	s_nop 1
	v_cndmask_b32_e32 v0, v22, v0, vcc
	v_div_scale_f32 v22, s[2:3], v0, v0, 1.0
	v_rcp_f32_e32 v23, v22
	s_nop 0
	v_fma_f32 v24, -v22, v23, 1.0
	v_fmac_f32_e32 v23, v24, v23
	v_div_scale_f32 v24, vcc, 1.0, v0, 1.0
	v_mul_f32_e32 v25, v24, v23
	v_fma_f32 v28, -v22, v25, v24
	v_fmac_f32_e32 v25, v28, v23
	v_fma_f32 v22, -v22, v25, v24
	v_div_fmas_f32 v22, v22, v23, v25
	v_div_fixup_f32 v0, v22, v0, 1.0
	v_pk_mul_f32 v[22:23], v[18:19], v[0:1] op_sel_hi:[1,0]
	v_pk_mul_f32 v[18:19], v[20:21], v[0:1] op_sel_hi:[1,0]
	v_pk_mul_f32 v[20:21], v[164:165], v[22:23]
	v_pk_mul_f32 v[22:23], v[10:11], v[0:1] op_sel_hi:[1,0]
	v_pk_mul_f32 v[10:11], v[12:13], v[0:1] op_sel_hi:[1,0]
	v_pk_mul_f32 v[12:13], v[6:7], v[0:1] op_sel_hi:[1,0]
	v_pk_mul_f32 v[6:7], v[8:9], v[0:1] op_sel_hi:[1,0]
	v_pk_mul_f32 v[2:3], v[2:3], v[0:1] op_sel_hi:[1,0]
	v_pk_mul_f32 v[4:5], v[4:5], v[0:1] op_sel_hi:[1,0]
	v_cndmask_b32_e64 v0, v26, v27, s[0:1]
	v_pk_mul_f32 v[18:19], v[162:163], v[18:19]
	v_pk_mul_f32 v[10:11], v[158:159], v[10:11]
	v_pk_mul_f32 v[22:23], v[160:161], v[22:23]
	v_pk_mul_f32 v[6:7], v[138:139], v[6:7]
	v_pk_mul_f32 v[12:13], v[140:141], v[12:13]
	v_pk_mul_f32 v[8:9], v[134:135], v[4:5]
	v_pk_mul_f32 v[24:25], v[136:137], v[2:3]
	v_cmp_gt_i32_e32 vcc, s66, v0
	s_and_saveexec_b64 s[0:1], vcc
	s_cbranch_execz .LBB0_274
	v_ashrrev_i32_e32 v2, 2, v0
	v_and_b32_e32 v2, -16, v2
	v_ashrrev_i32_e32 v3, 31, v2
	v_lshlrev_b64 v[2:3], 2, v[2:3]
	v_lshl_add_u64 v[32:33], v[150:151], 0, v[2:3]
	v_lshl_add_u64 v[34:35], v[152:153], 0, v[2:3]
	flat_load_dwordx4 v[2:5], v[32:33]
	flat_load_dwordx4 v[28:31], v[34:35]
	flat_load_dwordx4 v[240:243], v[32:33] offset:16
	flat_load_dwordx4 v[244:247], v[34:35] offset:16
	ds_bpermute_b32 v36, v174, v20
	ds_bpermute_b32 v37, v174, v21
	ds_bpermute_b32 v38, v174, v18
	ds_bpermute_b32 v39, v174, v19
	v_lshlrev_b32_e32 v0, 6, v0
	v_and_b32_e32 v0, 0xfc0, v0
	s_waitcnt vmcnt(0) lgkmcnt(0)
	v_xor_b32_e32 v27, 0x80000000, v28
	v_xor_b32_e32 v40, 0x80000000, v29
	v_xor_b32_e32 v41, 0x80000000, v30
	v_xor_b32_e32 v42, 0x80000000, v31
	v_cndmask_b32_e64 v31, v31, v42, s[4:5]
	v_cndmask_b32_e64 v30, v30, v41, s[4:5]
	v_cndmask_b32_e64 v29, v29, v40, s[4:5]
	v_cndmask_b32_e64 v28, v28, v27, s[4:5]
	v_pk_mul_f32 v[28:29], v[28:29], v[36:37]
	v_pk_mul_f32 v[30:31], v[30:31], v[38:39]
	v_pk_fma_f32 v[20:21], v[20:21], v[2:3], v[28:29]
	v_pk_fma_f32 v[18:19], v[18:19], v[4:5], v[30:31]
	ds_bpermute_b32 v32, v174, v22
	ds_bpermute_b32 v33, v174, v23
	ds_bpermute_b32 v34, v174, v10
	ds_bpermute_b32 v35, v174, v11
	ds_bpermute_b32 v39, v174, v7
	s_waitcnt vmcnt(0) lgkmcnt(0)
	v_xor_b32_e32 v27, 0x80000000, v244
	v_xor_b32_e32 v36, 0x80000000, v245
	v_xor_b32_e32 v37, 0x80000000, v246
	v_xor_b32_e32 v38, 0x80000000, v247
	v_cndmask_b32_e64 v247, v247, v38, s[4:5]
	v_cndmask_b32_e64 v246, v246, v37, s[4:5]
	v_cndmask_b32_e64 v245, v245, v36, s[4:5]
	v_cndmask_b32_e64 v244, v244, v27, s[4:5]
	v_pk_mul_f32 v[244:245], v[244:245], v[32:33]
	v_pk_mul_f32 v[246:247], v[246:247], v[34:35]
	v_lshl_add_u64 v[32:33], v[150:151], 0, v[0:1]
	v_pk_fma_f32 v[10:11], v[10:11], v[242:243], v[246:247]
	v_pk_fma_f32 v[22:23], v[22:23], v[240:241], v[244:245]
	v_lshl_add_u64 v[34:35], v[152:153], 0, v[0:1]
	flat_load_dwordx4 v[2:5], v[32:33]
	flat_load_dwordx4 v[28:31], v[34:35]
	flat_load_dwordx4 v[240:243], v[32:33] offset:16
	flat_load_dwordx4 v[244:247], v[34:35] offset:16
	ds_bpermute_b32 v36, v174, v12
	ds_bpermute_b32 v37, v174, v13
	ds_bpermute_b32 v38, v174, v6
	s_waitcnt vmcnt(0) lgkmcnt(0)
	v_xor_b32_e32 v0, 0x80000000, v28
	v_xor_b32_e32 v27, 0x80000000, v29
	v_xor_b32_e32 v40, 0x80000000, v30
	v_xor_b32_e32 v41, 0x80000000, v31
	v_cndmask_b32_e64 v31, v31, v41, s[4:5]
	v_cndmask_b32_e64 v30, v30, v40, s[4:5]
	v_cndmask_b32_e64 v29, v29, v27, s[4:5]
	v_cndmask_b32_e64 v28, v28, v0, s[4:5]
	v_pk_mul_f32 v[28:29], v[28:29], v[36:37]
	v_pk_mul_f32 v[30:31], v[30:31], v[38:39]
	v_pk_fma_f32 v[12:13], v[12:13], v[2:3], v[28:29]
	v_pk_fma_f32 v[6:7], v[6:7], v[4:5], v[30:31]
	ds_bpermute_b32 v32, v174, v24
	ds_bpermute_b32 v33, v174, v25
	ds_bpermute_b32 v34, v174, v8
	ds_bpermute_b32 v35, v174, v9
	s_waitcnt vmcnt(0) lgkmcnt(0)
	v_xor_b32_e32 v0, 0x80000000, v244
	v_xor_b32_e32 v27, 0x80000000, v245
	v_xor_b32_e32 v36, 0x80000000, v246
	v_xor_b32_e32 v37, 0x80000000, v247
	v_cndmask_b32_e64 v247, v247, v37, s[4:5]
	v_cndmask_b32_e64 v246, v246, v36, s[4:5]
	v_cndmask_b32_e64 v245, v245, v27, s[4:5]
	v_cndmask_b32_e64 v244, v244, v0, s[4:5]
	v_pk_mul_f32 v[244:245], v[244:245], v[32:33]
	v_pk_mul_f32 v[246:247], v[246:247], v[34:35]
	v_pk_fma_f32 v[24:25], v[24:25], v[240:241], v[244:245]
	v_pk_fma_f32 v[8:9], v[8:9], v[242:243], v[246:247]
